# lean G2 mq epilogue (scalar-branch rope path, packed stores); norm1/norm2 loops no longer drain previous-row stores before next-row loads
# speedup vs baseline: 1.0220x; 1.0058x over previous
.LBB0_256:
	s_andn2_b64 vcc, exec, s[0:1]
	s_cbranch_vccnz .LBB0_793
	s_cmp_gt_i32 s72, 6
	s_mov_b64 s[0:1], -1
	s_cbranch_scc0 .LBB0_264
	v_mov_b32_e32 v16, v224
	v_readlane_b32 s0, v251, 12
	v_ashrrev_i32_e32 v0, 6, v16
	s_nop 0
	v_add_u32_e32 v44, s0, v0
	s_movk_i32 s0, 0x3000
	v_cmp_gt_i32_e32 vcc, s0, v44
	s_and_saveexec_b64 s[4:5], vcc
	s_cbranch_execz .LBB0_263
	v_ashrrev_i32_e32 v45, 31, v44
	v_lshlrev_b32_e32 v2, 2, v16
	v_lshlrev_b64 v[0:1], 12, v[44:45]
	v_and_b32_e32 v18, 0xfc, v2
	v_lshl_add_u64 v[0:1], s[68:69], 0, v[0:1]
	v_lshlrev_b32_e32 v128, 2, v18
	v_lshl_add_u64 v[0:1], v[0:1], 0, v[128:129]
	global_load_dwordx4 v[12:15], v[0:1], off nt
	global_load_dwordx4 v[8:11], v[0:1], off offset:1024 nt
	global_load_dwordx4 v[4:7], v[0:1], off offset:2048 nt
	s_nop 0
	global_load_dwordx4 v[0:3], v[0:1], off offset:3072 nt
	v_and_b32_e32 v17, 64, v226
	v_add_u32_e32 v17, 64, v17
	v_xor_b32_e32 v19, 32, v226
	v_cmp_lt_i32_e32 vcc, v19, v17
	s_load_dword s0, s[24:25], 0x0
	v_or_b32_e32 v20, 0x100, v18
	v_cndmask_b32_e32 v19, v226, v19, vcc
	v_lshlrev_b32_e32 v47, 2, v19
	v_xor_b32_e32 v19, 16, v226
	v_cmp_lt_i32_e32 vcc, v19, v17
	s_waitcnt lgkmcnt(0)
	s_lshl_b32 s36, s0, 3
	v_readlane_b32 s0, v254, 26
	v_cndmask_b32_e32 v19, v226, v19, vcc
	v_lshlrev_b32_e32 v48, 2, v19
	v_xor_b32_e32 v19, 8, v226
	v_cmp_lt_i32_e32 vcc, v19, v17
	v_readlane_b32 s1, v254, 27
	v_add_u32_e32 v26, s36, v44
	v_cndmask_b32_e32 v19, v226, v19, vcc
	v_lshlrev_b32_e32 v49, 2, v19
	v_xor_b32_e32 v19, 4, v226
	v_cmp_lt_i32_e32 vcc, v19, v17
	v_lshl_add_u64 v[32:33], s[0:1], 0, v[128:129]
	v_ashrrev_i32_e32 v27, 31, v26
	v_cndmask_b32_e32 v19, v226, v19, vcc
	v_lshlrev_b32_e32 v50, 2, v19
	v_xor_b32_e32 v19, 2, v226
	v_cmp_lt_i32_e32 vcc, v19, v17
	v_readlane_b32 s0, v253, 29
	v_lshlrev_b64 v[26:27], 12, v[26:27]
	v_cndmask_b32_e32 v19, v226, v19, vcc
	v_lshlrev_b32_e32 v51, 2, v19
	v_xor_b32_e32 v19, 1, v226
	v_cmp_lt_i32_e32 vcc, v19, v17
	s_add_u32 s0, s0, s30
	v_readlane_b32 s1, v253, 30
	v_cndmask_b32_e32 v17, v226, v19, vcc
	v_and_b32_e32 v19, 63, v16
	v_lshlrev_b32_e32 v52, 2, v17
	v_lshl_or_b32 v26, v19, 4, v26
	s_addc_u32 s1, s1, s31
	v_lshlrev_b64 v[16:17], 11, v[44:45]
	v_lshl_add_u64 v[34:35], s[0:1], 0, v[26:27]
	v_lshl_add_u64 v[16:17], s[74:75], 0, v[16:17]
	v_lshlrev_b32_e32 v128, 3, v19
	v_readlane_b32 s0, v253, 31
	v_or_b32_e32 v22, 0x200, v18
	v_or_b32_e32 v24, 0x300, v18
	s_ashr_i32 s37, s36, 31
	v_lshl_add_u64 v[16:17], v[16:17], 0, v[128:129]
	v_readlane_b32 s1, v253, 32
	s_lshl_b64 s[30:31], s[36:37], 12
	s_lshl_b64 s[38:39], s[36:37], 11
	v_lshl_add_u64 v[36:37], s[0:1], 0, v[16:17]
	s_mov_b64 s[40:41], 0
	v_lshlrev_b32_e32 v128, 2, v18
	v_lshlrev_b32_e32 v38, 2, v20
	v_lshlrev_b32_e32 v40, 2, v22
	v_lshlrev_b32_e32 v42, 2, v24
	s_waitcnt vmcnt(0)
	s_branch .LBB0_261

.LBB0_261:
	v_add_u32_e32 v45, s36, v44
	s_movk_i32 s0, 0x3000
	v_cmp_gt_i32_e64 s[0:1], s0, v45
	v_cmp_lt_i32_e32 vcc, s92, v45
	s_waitcnt vmcnt(4)
	v_mov_b32_e32 v16, v12
	v_mov_b32_e32 v17, v13
	v_mov_b32_e32 v18, v14
	v_mov_b32_e32 v19, v15
	v_mov_b32_e32 v20, v8
	v_mov_b32_e32 v21, v9
	v_mov_b32_e32 v22, v10
	v_mov_b32_e32 v23, v11
	v_mov_b32_e32 v24, v4
	v_mov_b32_e32 v25, v5
	v_mov_b32_e32 v26, v6
	v_mov_b32_e32 v27, v7
	v_mov_b32_e32 v28, v0
	v_mov_b32_e32 v29, v1
	v_mov_b32_e32 v30, v2
	v_mov_b32_e32 v31, v3
	s_and_saveexec_b64 s[6:7], s[0:1]
	s_cbranch_execz .LBB0_260
	global_load_dwordx4 v[16:19], v[34:35], off offset:-2048 nt
	global_load_dwordx4 v[20:23], v[34:35], off offset:-1024 nt
	global_load_dwordx4 v[24:27], v[34:35], off nt
	global_load_dwordx4 v[28:31], v[34:35], off offset:1024 nt
	s_branch .LBB0_260

.LBB0_1277:
	s_and_b64 vcc, exec, s[4:5]
	s_cbranch_vccz .LBB0_1223
	v_readfirstlane_b32 s4, v143
	s_nop 3
	s_add_i32 s4, s4, s54
	s_cmpk_ge_i32 s4, 0x180
	s_cbranch_scc1 .LBB0_1223
	v_add_u32_e32 v148, s55, v178
	v_or_b32_e32 v149, s54, v143
	v_or_b32_e32 v144, v149, v141
	v_mul_u32_u24_e32 v145, 0x300, v148
	v_lshl_add_u32 v145, v144, 1, v145
	s_nop 7
	s_and_b64 vcc, exec, s[0:1]
	s_cbranch_vccz .Lmq_plain_all
	s_cmpk_eq_i32 s4, 0x40
	s_cbranch_scc1 .Lmq_rope0
	s_cmpk_eq_i32 s4, 0x100
	s_cbranch_scc1 .Lmq_rope0
	s_cmpk_eq_i32 s4, 0x80
	s_cbranch_scc1 .Lmq_rope1
	s_cmpk_eq_i32 s4, 0x140
	s_cbranch_scc1 .Lmq_rope1
.Lmq_plain_all:
	v_mul_f32_e32 v112, 0x3e16c740, v112
	v_mul_f32_e32 v113, 0x3e16c740, v113
	v_cvt_pk_bf16_f32 v112, v112, v113
	v_mul_f32_e32 v114, 0x3e16c740, v114
	v_mul_f32_e32 v115, 0x3e16c740, v115
	v_cvt_pk_bf16_f32 v114, v114, v115
	v_mul_f32_e32 v116, 0x3e16c740, v116
	v_mul_f32_e32 v117, 0x3e16c740, v117
	v_cvt_pk_bf16_f32 v116, v116, v117
	v_mul_f32_e32 v118, 0x3e16c740, v118
	v_mul_f32_e32 v119, 0x3e16c740, v119
	v_cvt_pk_bf16_f32 v118, v118, v119
	v_mul_f32_e32 v120, 0x3e16c740, v120
	v_mul_f32_e32 v121, 0x3e16c740, v121
	v_cvt_pk_bf16_f32 v120, v120, v121
	v_mul_f32_e32 v122, 0x3e16c740, v122
	v_mul_f32_e32 v123, 0x3e16c740, v123
	v_cvt_pk_bf16_f32 v122, v122, v123
	v_mul_f32_e32 v124, 0x3e16c740, v124
	v_mul_f32_e32 v125, 0x3e16c740, v125
	v_cvt_pk_bf16_f32 v124, v124, v125
	v_mul_f32_e32 v126, 0x3e16c740, v126
	v_mul_f32_e32 v127, 0x3e16c740, v127
	v_cvt_pk_bf16_f32 v126, v126, v127
	s_mov_b32 s4, s70
	s_mov_b32 s5, s71
	global_store_short v145, v112, s[4:5]
	s_add_u32 s4, s4, 0x300
	s_addc_u32 s5, s5, 0
	global_store_short_d16_hi v145, v112, s[4:5]
	s_add_u32 s4, s70, 0x600
	s_addc_u32 s5, s71, 0
	global_store_short v145, v114, s[4:5]
	s_add_u32 s4, s4, 0x300
	s_addc_u32 s5, s5, 0
	global_store_short_d16_hi v145, v114, s[4:5]
	s_add_u32 s4, s70, 0x1800
	s_addc_u32 s5, s71, 0
	global_store_short v145, v116, s[4:5]
	s_add_u32 s4, s4, 0x300
	s_addc_u32 s5, s5, 0
	global_store_short_d16_hi v145, v116, s[4:5]
	s_add_u32 s4, s70, 0x1e00
	s_addc_u32 s5, s71, 0
	global_store_short v145, v118, s[4:5]
	s_add_u32 s4, s4, 0x300
	s_addc_u32 s5, s5, 0
	global_store_short_d16_hi v145, v118, s[4:5]
	s_add_u32 s4, s70, 0x3000
	s_addc_u32 s5, s71, 0
	global_store_short v145, v120, s[4:5]
	s_add_u32 s4, s4, 0x300
	s_addc_u32 s5, s5, 0
	global_store_short_d16_hi v145, v120, s[4:5]
	s_add_u32 s4, s70, 0x3600
	s_addc_u32 s5, s71, 0
	global_store_short v145, v122, s[4:5]
	s_add_u32 s4, s4, 0x300
	s_addc_u32 s5, s5, 0
	global_store_short_d16_hi v145, v122, s[4:5]
	s_add_u32 s4, s70, 0x4800
	s_addc_u32 s5, s71, 0
	global_store_short v145, v124, s[4:5]
	s_add_u32 s4, s4, 0x300
	s_addc_u32 s5, s5, 0
	global_store_short_d16_hi v145, v124, s[4:5]
	s_add_u32 s4, s70, 0x4e00
	s_addc_u32 s5, s71, 0
	global_store_short v145, v126, s[4:5]
	s_add_u32 s4, s4, 0x300
	s_addc_u32 s5, s5, 0
	global_store_short_d16_hi v145, v126, s[4:5]
	v_mul_f32_e32 v96, 0x3e16c740, v96
	v_mul_f32_e32 v97, 0x3e16c740, v97
	v_cvt_pk_bf16_f32 v96, v96, v97
	v_mul_f32_e32 v98, 0x3e16c740, v98
	v_mul_f32_e32 v99, 0x3e16c740, v99
	v_cvt_pk_bf16_f32 v98, v98, v99
	v_mul_f32_e32 v100, 0x3e16c740, v100
	v_mul_f32_e32 v101, 0x3e16c740, v101
	v_cvt_pk_bf16_f32 v100, v100, v101
	v_mul_f32_e32 v102, 0x3e16c740, v102
	v_mul_f32_e32 v103, 0x3e16c740, v103
	v_cvt_pk_bf16_f32 v102, v102, v103
	v_mul_f32_e32 v104, 0x3e16c740, v104
	v_mul_f32_e32 v105, 0x3e16c740, v105
	v_cvt_pk_bf16_f32 v104, v104, v105
	v_mul_f32_e32 v106, 0x3e16c740, v106
	v_mul_f32_e32 v107, 0x3e16c740, v107
	v_cvt_pk_bf16_f32 v106, v106, v107
	v_mul_f32_e32 v108, 0x3e16c740, v108
	v_mul_f32_e32 v109, 0x3e16c740, v109
	v_cvt_pk_bf16_f32 v108, v108, v109
	v_mul_f32_e32 v110, 0x3e16c740, v110
	v_mul_f32_e32 v111, 0x3e16c740, v111
	v_cvt_pk_bf16_f32 v110, v110, v111
	s_mov_b32 s4, s70
	s_mov_b32 s5, s71
	global_store_short v145, v96, s[4:5] offset:64
	s_add_u32 s4, s4, 0x300
	s_addc_u32 s5, s5, 0
	global_store_short_d16_hi v145, v96, s[4:5] offset:64
	s_add_u32 s4, s70, 0x600
	s_addc_u32 s5, s71, 0
	global_store_short v145, v98, s[4:5] offset:64
	s_add_u32 s4, s4, 0x300
	s_addc_u32 s5, s5, 0
	global_store_short_d16_hi v145, v98, s[4:5] offset:64
	s_add_u32 s4, s70, 0x1800
	s_addc_u32 s5, s71, 0
	global_store_short v145, v100, s[4:5] offset:64
	s_add_u32 s4, s4, 0x300
	s_addc_u32 s5, s5, 0
	global_store_short_d16_hi v145, v100, s[4:5] offset:64
	s_add_u32 s4, s70, 0x1e00
	s_addc_u32 s5, s71, 0
	global_store_short v145, v102, s[4:5] offset:64
	s_add_u32 s4, s4, 0x300
	s_addc_u32 s5, s5, 0
	global_store_short_d16_hi v145, v102, s[4:5] offset:64
	s_add_u32 s4, s70, 0x3000
	s_addc_u32 s5, s71, 0
	global_store_short v145, v104, s[4:5] offset:64
	s_add_u32 s4, s4, 0x300
	s_addc_u32 s5, s5, 0
	global_store_short_d16_hi v145, v104, s[4:5] offset:64
	s_add_u32 s4, s70, 0x3600
	s_addc_u32 s5, s71, 0
	global_store_short v145, v106, s[4:5] offset:64
	s_add_u32 s4, s4, 0x300
	s_addc_u32 s5, s5, 0
	global_store_short_d16_hi v145, v106, s[4:5] offset:64
	s_add_u32 s4, s70, 0x4800
	s_addc_u32 s5, s71, 0
	global_store_short v145, v108, s[4:5] offset:64
	s_add_u32 s4, s4, 0x300
	s_addc_u32 s5, s5, 0
	global_store_short_d16_hi v145, v108, s[4:5] offset:64
	s_add_u32 s4, s70, 0x4e00
	s_addc_u32 s5, s71, 0
	global_store_short v145, v110, s[4:5] offset:64
	s_add_u32 s4, s4, 0x300
	s_addc_u32 s5, s5, 0
	global_store_short_d16_hi v145, v110, s[4:5] offset:64
	v_mul_f32_e32 v80, 0x3e16c740, v80
	v_mul_f32_e32 v81, 0x3e16c740, v81
	v_cvt_pk_bf16_f32 v80, v80, v81
	v_mul_f32_e32 v82, 0x3e16c740, v82
	v_mul_f32_e32 v83, 0x3e16c740, v83
	v_cvt_pk_bf16_f32 v82, v82, v83
	v_mul_f32_e32 v84, 0x3e16c740, v84
	v_mul_f32_e32 v85, 0x3e16c740, v85
	v_cvt_pk_bf16_f32 v84, v84, v85
	v_mul_f32_e32 v86, 0x3e16c740, v86
	v_mul_f32_e32 v87, 0x3e16c740, v87
	v_cvt_pk_bf16_f32 v86, v86, v87
	v_mul_f32_e32 v88, 0x3e16c740, v88
	v_mul_f32_e32 v89, 0x3e16c740, v89
	v_cvt_pk_bf16_f32 v88, v88, v89
	v_mul_f32_e32 v90, 0x3e16c740, v90
	v_mul_f32_e32 v91, 0x3e16c740, v91
	v_cvt_pk_bf16_f32 v90, v90, v91
	v_mul_f32_e32 v92, 0x3e16c740, v92
	v_mul_f32_e32 v93, 0x3e16c740, v93
	v_cvt_pk_bf16_f32 v92, v92, v93
	v_mul_f32_e32 v94, 0x3e16c740, v94
	v_mul_f32_e32 v95, 0x3e16c740, v95
	v_cvt_pk_bf16_f32 v94, v94, v95
	s_add_u32 s4, s70, 0x6000
	s_addc_u32 s5, s71, 0
	global_store_short v145, v80, s[4:5]
	s_add_u32 s4, s4, 0x300
	s_addc_u32 s5, s5, 0
	global_store_short_d16_hi v145, v80, s[4:5]
	s_add_u32 s4, s70, 0x6600
	s_addc_u32 s5, s71, 0
	global_store_short v145, v82, s[4:5]
	s_add_u32 s4, s4, 0x300
	s_addc_u32 s5, s5, 0
	global_store_short_d16_hi v145, v82, s[4:5]
	s_add_u32 s4, s70, 0x7800
	s_addc_u32 s5, s71, 0
	global_store_short v145, v84, s[4:5]
	s_add_u32 s4, s4, 0x300
	s_addc_u32 s5, s5, 0
	global_store_short_d16_hi v145, v84, s[4:5]
	s_add_u32 s4, s70, 0x7e00
	s_addc_u32 s5, s71, 0
	global_store_short v145, v86, s[4:5]
	s_add_u32 s4, s4, 0x300
	s_addc_u32 s5, s5, 0
	global_store_short_d16_hi v145, v86, s[4:5]
	s_add_u32 s4, s70, 0x9000
	s_addc_u32 s5, s71, 0
	global_store_short v145, v88, s[4:5]
	s_add_u32 s4, s4, 0x300
	s_addc_u32 s5, s5, 0
	global_store_short_d16_hi v145, v88, s[4:5]
	s_add_u32 s4, s70, 0x9600
	s_addc_u32 s5, s71, 0
	global_store_short v145, v90, s[4:5]
	s_add_u32 s4, s4, 0x300
	s_addc_u32 s5, s5, 0
	global_store_short_d16_hi v145, v90, s[4:5]
	s_add_u32 s4, s70, 0xa800
	s_addc_u32 s5, s71, 0
	global_store_short v145, v92, s[4:5]
	s_add_u32 s4, s4, 0x300
	s_addc_u32 s5, s5, 0
	global_store_short_d16_hi v145, v92, s[4:5]
	s_add_u32 s4, s70, 0xae00
	s_addc_u32 s5, s71, 0
	global_store_short v145, v94, s[4:5]
	s_add_u32 s4, s4, 0x300
	s_addc_u32 s5, s5, 0
	global_store_short_d16_hi v145, v94, s[4:5]
	v_mul_f32_e32 v64, 0x3e16c740, v64
	v_mul_f32_e32 v65, 0x3e16c740, v65
	v_cvt_pk_bf16_f32 v64, v64, v65
	v_mul_f32_e32 v66, 0x3e16c740, v66
	v_mul_f32_e32 v67, 0x3e16c740, v67
	v_cvt_pk_bf16_f32 v66, v66, v67
	v_mul_f32_e32 v68, 0x3e16c740, v68
	v_mul_f32_e32 v69, 0x3e16c740, v69
	v_cvt_pk_bf16_f32 v68, v68, v69
	v_mul_f32_e32 v70, 0x3e16c740, v70
	v_mul_f32_e32 v71, 0x3e16c740, v71
	v_cvt_pk_bf16_f32 v70, v70, v71
	v_mul_f32_e32 v72, 0x3e16c740, v72
	v_mul_f32_e32 v73, 0x3e16c740, v73
	v_cvt_pk_bf16_f32 v72, v72, v73
	v_mul_f32_e32 v74, 0x3e16c740, v74
	v_mul_f32_e32 v75, 0x3e16c740, v75
	v_cvt_pk_bf16_f32 v74, v74, v75
	v_mul_f32_e32 v76, 0x3e16c740, v76
	v_mul_f32_e32 v77, 0x3e16c740, v77
	v_cvt_pk_bf16_f32 v76, v76, v77
	v_mul_f32_e32 v78, 0x3e16c740, v78
	v_mul_f32_e32 v79, 0x3e16c740, v79
	v_cvt_pk_bf16_f32 v78, v78, v79
	s_add_u32 s4, s70, 0x6000
	s_addc_u32 s5, s71, 0
	global_store_short v145, v64, s[4:5] offset:64
	s_add_u32 s4, s4, 0x300
	s_addc_u32 s5, s5, 0
	global_store_short_d16_hi v145, v64, s[4:5] offset:64
	s_add_u32 s4, s70, 0x6600
	s_addc_u32 s5, s71, 0
	global_store_short v145, v66, s[4:5] offset:64
	s_add_u32 s4, s4, 0x300
	s_addc_u32 s5, s5, 0
	global_store_short_d16_hi v145, v66, s[4:5] offset:64
	s_add_u32 s4, s70, 0x7800
	s_addc_u32 s5, s71, 0
	global_store_short v145, v68, s[4:5] offset:64
	s_add_u32 s4, s4, 0x300
	s_addc_u32 s5, s5, 0
	global_store_short_d16_hi v145, v68, s[4:5] offset:64
	s_add_u32 s4, s70, 0x7e00
	s_addc_u32 s5, s71, 0
	global_store_short v145, v70, s[4:5] offset:64
	s_add_u32 s4, s4, 0x300
	s_addc_u32 s5, s5, 0
	global_store_short_d16_hi v145, v70, s[4:5] offset:64
	s_add_u32 s4, s70, 0x9000
	s_addc_u32 s5, s71, 0
	global_store_short v145, v72, s[4:5] offset:64
	s_add_u32 s4, s4, 0x300
	s_addc_u32 s5, s5, 0
	global_store_short_d16_hi v145, v72, s[4:5] offset:64
	s_add_u32 s4, s70, 0x9600
	s_addc_u32 s5, s71, 0
	global_store_short v145, v74, s[4:5] offset:64
	s_add_u32 s4, s4, 0x300
	s_addc_u32 s5, s5, 0
	global_store_short_d16_hi v145, v74, s[4:5] offset:64
	s_add_u32 s4, s70, 0xa800
	s_addc_u32 s5, s71, 0
	global_store_short v145, v76, s[4:5] offset:64
	s_add_u32 s4, s4, 0x300
	s_addc_u32 s5, s5, 0
	global_store_short_d16_hi v145, v76, s[4:5] offset:64
	s_add_u32 s4, s70, 0xae00
	s_addc_u32 s5, s71, 0
	global_store_short v145, v78, s[4:5] offset:64
	s_add_u32 s4, s4, 0x300
	s_addc_u32 s5, s5, 0
	global_store_short_d16_hi v145, v78, s[4:5] offset:64
	v_mul_f32_e32 v48, 0x3e16c740, v48
	v_mul_f32_e32 v49, 0x3e16c740, v49
	v_cvt_pk_bf16_f32 v48, v48, v49
	v_mul_f32_e32 v50, 0x3e16c740, v50
	v_mul_f32_e32 v51, 0x3e16c740, v51
	v_cvt_pk_bf16_f32 v50, v50, v51
	v_mul_f32_e32 v52, 0x3e16c740, v52
	v_mul_f32_e32 v53, 0x3e16c740, v53
	v_cvt_pk_bf16_f32 v52, v52, v53
	v_mul_f32_e32 v54, 0x3e16c740, v54
	v_mul_f32_e32 v55, 0x3e16c740, v55
	v_cvt_pk_bf16_f32 v54, v54, v55
	v_mul_f32_e32 v56, 0x3e16c740, v56
	v_mul_f32_e32 v57, 0x3e16c740, v57
	v_cvt_pk_bf16_f32 v56, v56, v57
	v_mul_f32_e32 v58, 0x3e16c740, v58
	v_mul_f32_e32 v59, 0x3e16c740, v59
	v_cvt_pk_bf16_f32 v58, v58, v59
	v_mul_f32_e32 v60, 0x3e16c740, v60
	v_mul_f32_e32 v61, 0x3e16c740, v61
	v_cvt_pk_bf16_f32 v60, v60, v61
	v_mul_f32_e32 v62, 0x3e16c740, v62
	v_mul_f32_e32 v63, 0x3e16c740, v63
	v_cvt_pk_bf16_f32 v62, v62, v63
	s_add_u32 s4, s70, 0xc000
	s_addc_u32 s5, s71, 0
	global_store_short v145, v48, s[4:5]
	s_add_u32 s4, s4, 0x300
	s_addc_u32 s5, s5, 0
	global_store_short_d16_hi v145, v48, s[4:5]
	s_add_u32 s4, s70, 0xc600
	s_addc_u32 s5, s71, 0
	global_store_short v145, v50, s[4:5]
	s_add_u32 s4, s4, 0x300
	s_addc_u32 s5, s5, 0
	global_store_short_d16_hi v145, v50, s[4:5]
	s_add_u32 s4, s70, 0xd800
	s_addc_u32 s5, s71, 0
	global_store_short v145, v52, s[4:5]
	s_add_u32 s4, s4, 0x300
	s_addc_u32 s5, s5, 0
	global_store_short_d16_hi v145, v52, s[4:5]
	s_add_u32 s4, s70, 0xde00
	s_addc_u32 s5, s71, 0
	global_store_short v145, v54, s[4:5]
	s_add_u32 s4, s4, 0x300
	s_addc_u32 s5, s5, 0
	global_store_short_d16_hi v145, v54, s[4:5]
	s_add_u32 s4, s70, 0xf000
	s_addc_u32 s5, s71, 0
	global_store_short v145, v56, s[4:5]
	s_add_u32 s4, s4, 0x300
	s_addc_u32 s5, s5, 0
	global_store_short_d16_hi v145, v56, s[4:5]
	s_add_u32 s4, s70, 0xf600
	s_addc_u32 s5, s71, 0
	global_store_short v145, v58, s[4:5]
	s_add_u32 s4, s4, 0x300
	s_addc_u32 s5, s5, 0
	global_store_short_d16_hi v145, v58, s[4:5]
	s_add_u32 s4, s70, 0x10800
	s_addc_u32 s5, s71, 0
	global_store_short v145, v60, s[4:5]
	s_add_u32 s4, s4, 0x300
	s_addc_u32 s5, s5, 0
	global_store_short_d16_hi v145, v60, s[4:5]
	s_add_u32 s4, s70, 0x10e00
	s_addc_u32 s5, s71, 0
	global_store_short v145, v62, s[4:5]
	s_add_u32 s4, s4, 0x300
	s_addc_u32 s5, s5, 0
	global_store_short_d16_hi v145, v62, s[4:5]
	v_mul_f32_e32 v32, 0x3e16c740, v32
	v_mul_f32_e32 v33, 0x3e16c740, v33
	v_cvt_pk_bf16_f32 v32, v32, v33
	v_mul_f32_e32 v34, 0x3e16c740, v34
	v_mul_f32_e32 v35, 0x3e16c740, v35
	v_cvt_pk_bf16_f32 v34, v34, v35
	v_mul_f32_e32 v36, 0x3e16c740, v36
	v_mul_f32_e32 v37, 0x3e16c740, v37
	v_cvt_pk_bf16_f32 v36, v36, v37
	v_mul_f32_e32 v38, 0x3e16c740, v38
	v_mul_f32_e32 v39, 0x3e16c740, v39
	v_cvt_pk_bf16_f32 v38, v38, v39
	v_mul_f32_e32 v40, 0x3e16c740, v40
	v_mul_f32_e32 v41, 0x3e16c740, v41
	v_cvt_pk_bf16_f32 v40, v40, v41
	v_mul_f32_e32 v42, 0x3e16c740, v42
	v_mul_f32_e32 v43, 0x3e16c740, v43
	v_cvt_pk_bf16_f32 v42, v42, v43
	v_mul_f32_e32 v44, 0x3e16c740, v44
	v_mul_f32_e32 v45, 0x3e16c740, v45
	v_cvt_pk_bf16_f32 v44, v44, v45
	v_mul_f32_e32 v46, 0x3e16c740, v46
	v_mul_f32_e32 v47, 0x3e16c740, v47
	v_cvt_pk_bf16_f32 v46, v46, v47
	s_add_u32 s4, s70, 0xc000
	s_addc_u32 s5, s71, 0
	global_store_short v145, v32, s[4:5] offset:64
	s_add_u32 s4, s4, 0x300
	s_addc_u32 s5, s5, 0
	global_store_short_d16_hi v145, v32, s[4:5] offset:64
	s_add_u32 s4, s70, 0xc600
	s_addc_u32 s5, s71, 0
	global_store_short v145, v34, s[4:5] offset:64
	s_add_u32 s4, s4, 0x300
	s_addc_u32 s5, s5, 0
	global_store_short_d16_hi v145, v34, s[4:5] offset:64
	s_add_u32 s4, s70, 0xd800
	s_addc_u32 s5, s71, 0
	global_store_short v145, v36, s[4:5] offset:64
	s_add_u32 s4, s4, 0x300
	s_addc_u32 s5, s5, 0
	global_store_short_d16_hi v145, v36, s[4:5] offset:64
	s_add_u32 s4, s70, 0xde00
	s_addc_u32 s5, s71, 0
	global_store_short v145, v38, s[4:5] offset:64
	s_add_u32 s4, s4, 0x300
	s_addc_u32 s5, s5, 0
	global_store_short_d16_hi v145, v38, s[4:5] offset:64
	s_add_u32 s4, s70, 0xf000
	s_addc_u32 s5, s71, 0
	global_store_short v145, v40, s[4:5] offset:64
	s_add_u32 s4, s4, 0x300
	s_addc_u32 s5, s5, 0
	global_store_short_d16_hi v145, v40, s[4:5] offset:64
	s_add_u32 s4, s70, 0xf600
	s_addc_u32 s5, s71, 0
	global_store_short v145, v42, s[4:5] offset:64
	s_add_u32 s4, s4, 0x300
	s_addc_u32 s5, s5, 0
	global_store_short_d16_hi v145, v42, s[4:5] offset:64
	s_add_u32 s4, s70, 0x10800
	s_addc_u32 s5, s71, 0
	global_store_short v145, v44, s[4:5] offset:64
	s_add_u32 s4, s4, 0x300
	s_addc_u32 s5, s5, 0
	global_store_short_d16_hi v145, v44, s[4:5] offset:64
	s_add_u32 s4, s70, 0x10e00
	s_addc_u32 s5, s71, 0
	global_store_short v145, v46, s[4:5] offset:64
	s_add_u32 s4, s4, 0x300
	s_addc_u32 s5, s5, 0
	global_store_short_d16_hi v145, v46, s[4:5] offset:64
	v_mul_f32_e32 v16, 0x3e16c740, v16
	v_mul_f32_e32 v17, 0x3e16c740, v17
	v_cvt_pk_bf16_f32 v16, v16, v17
	v_mul_f32_e32 v18, 0x3e16c740, v18
	v_mul_f32_e32 v19, 0x3e16c740, v19
	v_cvt_pk_bf16_f32 v18, v18, v19
	v_mul_f32_e32 v20, 0x3e16c740, v20
	v_mul_f32_e32 v21, 0x3e16c740, v21
	v_cvt_pk_bf16_f32 v20, v20, v21
	v_mul_f32_e32 v22, 0x3e16c740, v22
	v_mul_f32_e32 v23, 0x3e16c740, v23
	v_cvt_pk_bf16_f32 v22, v22, v23
	v_mul_f32_e32 v24, 0x3e16c740, v24
	v_mul_f32_e32 v25, 0x3e16c740, v25
	v_cvt_pk_bf16_f32 v24, v24, v25
	v_mul_f32_e32 v26, 0x3e16c740, v26
	v_mul_f32_e32 v27, 0x3e16c740, v27
	v_cvt_pk_bf16_f32 v26, v26, v27
	v_mul_f32_e32 v28, 0x3e16c740, v28
	v_mul_f32_e32 v29, 0x3e16c740, v29
	v_cvt_pk_bf16_f32 v28, v28, v29
	v_mul_f32_e32 v30, 0x3e16c740, v30
	v_mul_f32_e32 v31, 0x3e16c740, v31
	v_cvt_pk_bf16_f32 v30, v30, v31
	s_add_u32 s4, s70, 0x12000
	s_addc_u32 s5, s71, 0
	global_store_short v145, v16, s[4:5]
	s_add_u32 s4, s4, 0x300
	s_addc_u32 s5, s5, 0
	global_store_short_d16_hi v145, v16, s[4:5]
	s_add_u32 s4, s70, 0x12600
	s_addc_u32 s5, s71, 0
	global_store_short v145, v18, s[4:5]
	s_add_u32 s4, s4, 0x300
	s_addc_u32 s5, s5, 0
	global_store_short_d16_hi v145, v18, s[4:5]
	s_add_u32 s4, s70, 0x13800
	s_addc_u32 s5, s71, 0
	global_store_short v145, v20, s[4:5]
	s_add_u32 s4, s4, 0x300
	s_addc_u32 s5, s5, 0
	global_store_short_d16_hi v145, v20, s[4:5]
	s_add_u32 s4, s70, 0x13e00
	s_addc_u32 s5, s71, 0
	global_store_short v145, v22, s[4:5]
	s_add_u32 s4, s4, 0x300
	s_addc_u32 s5, s5, 0
	global_store_short_d16_hi v145, v22, s[4:5]
	s_add_u32 s4, s70, 0x15000
	s_addc_u32 s5, s71, 0
	global_store_short v145, v24, s[4:5]
	s_add_u32 s4, s4, 0x300
	s_addc_u32 s5, s5, 0
	global_store_short_d16_hi v145, v24, s[4:5]
	s_add_u32 s4, s70, 0x15600
	s_addc_u32 s5, s71, 0
	global_store_short v145, v26, s[4:5]
	s_add_u32 s4, s4, 0x300
	s_addc_u32 s5, s5, 0
	global_store_short_d16_hi v145, v26, s[4:5]
	s_add_u32 s4, s70, 0x16800
	s_addc_u32 s5, s71, 0
	global_store_short v145, v28, s[4:5]
	s_add_u32 s4, s4, 0x300
	s_addc_u32 s5, s5, 0
	global_store_short_d16_hi v145, v28, s[4:5]
	s_add_u32 s4, s70, 0x16e00
	s_addc_u32 s5, s71, 0
	global_store_short v145, v30, s[4:5]
	s_add_u32 s4, s4, 0x300
	s_addc_u32 s5, s5, 0
	global_store_short_d16_hi v145, v30, s[4:5]
	v_mul_f32_e32 v0, 0x3e16c740, v0
	v_mul_f32_e32 v1, 0x3e16c740, v1
	v_cvt_pk_bf16_f32 v0, v0, v1
	v_mul_f32_e32 v2, 0x3e16c740, v2
	v_mul_f32_e32 v3, 0x3e16c740, v3
	v_cvt_pk_bf16_f32 v2, v2, v3
	v_mul_f32_e32 v4, 0x3e16c740, v4
	v_mul_f32_e32 v5, 0x3e16c740, v5
	v_cvt_pk_bf16_f32 v4, v4, v5
	v_mul_f32_e32 v6, 0x3e16c740, v6
	v_mul_f32_e32 v7, 0x3e16c740, v7
	v_cvt_pk_bf16_f32 v6, v6, v7
	v_mul_f32_e32 v8, 0x3e16c740, v8
	v_mul_f32_e32 v9, 0x3e16c740, v9
	v_cvt_pk_bf16_f32 v8, v8, v9
	v_mul_f32_e32 v10, 0x3e16c740, v10
	v_mul_f32_e32 v11, 0x3e16c740, v11
	v_cvt_pk_bf16_f32 v10, v10, v11
	v_mul_f32_e32 v12, 0x3e16c740, v12
	v_mul_f32_e32 v13, 0x3e16c740, v13
	v_cvt_pk_bf16_f32 v12, v12, v13
	v_mul_f32_e32 v14, 0x3e16c740, v14
	v_mul_f32_e32 v15, 0x3e16c740, v15
	v_cvt_pk_bf16_f32 v14, v14, v15
	s_add_u32 s4, s70, 0x12000
	s_addc_u32 s5, s71, 0
	global_store_short v145, v0, s[4:5] offset:64
	s_add_u32 s4, s4, 0x300
	s_addc_u32 s5, s5, 0
	global_store_short_d16_hi v145, v0, s[4:5] offset:64
	s_add_u32 s4, s70, 0x12600
	s_addc_u32 s5, s71, 0
	global_store_short v145, v2, s[4:5] offset:64
	s_add_u32 s4, s4, 0x300
	s_addc_u32 s5, s5, 0
	global_store_short_d16_hi v145, v2, s[4:5] offset:64
	s_add_u32 s4, s70, 0x13800
	s_addc_u32 s5, s71, 0
	global_store_short v145, v4, s[4:5] offset:64
	s_add_u32 s4, s4, 0x300
	s_addc_u32 s5, s5, 0
	global_store_short_d16_hi v145, v4, s[4:5] offset:64
	s_add_u32 s4, s70, 0x13e00
	s_addc_u32 s5, s71, 0
	global_store_short v145, v6, s[4:5] offset:64
	s_add_u32 s4, s4, 0x300
	s_addc_u32 s5, s5, 0
	global_store_short_d16_hi v145, v6, s[4:5] offset:64
	s_add_u32 s4, s70, 0x15000
	s_addc_u32 s5, s71, 0
	global_store_short v145, v8, s[4:5] offset:64
	s_add_u32 s4, s4, 0x300
	s_addc_u32 s5, s5, 0
	global_store_short_d16_hi v145, v8, s[4:5] offset:64
	s_add_u32 s4, s70, 0x15600
	s_addc_u32 s5, s71, 0
	global_store_short v145, v10, s[4:5] offset:64
	s_add_u32 s4, s4, 0x300
	s_addc_u32 s5, s5, 0
	global_store_short_d16_hi v145, v10, s[4:5] offset:64
	s_add_u32 s4, s70, 0x16800
	s_addc_u32 s5, s71, 0
	global_store_short v145, v12, s[4:5] offset:64
	s_add_u32 s4, s4, 0x300
	s_addc_u32 s5, s5, 0
	global_store_short_d16_hi v145, v12, s[4:5] offset:64
	s_add_u32 s4, s70, 0x16e00
	s_addc_u32 s5, s71, 0
	global_store_short v145, v14, s[4:5] offset:64
	s_add_u32 s4, s4, 0x300
	s_addc_u32 s5, s5, 0
	global_store_short_d16_hi v145, v14, s[4:5] offset:64
	s_branch .LBB0_1223
.Lmq_rope0:
	v_mul_f32_e32 v96, 0x3e16c740, v96
	v_mul_f32_e32 v97, 0x3e16c740, v97
	v_cvt_pk_bf16_f32 v96, v96, v97
	v_mul_f32_e32 v98, 0x3e16c740, v98
	v_mul_f32_e32 v99, 0x3e16c740, v99
	v_cvt_pk_bf16_f32 v98, v98, v99
	v_mul_f32_e32 v100, 0x3e16c740, v100
	v_mul_f32_e32 v101, 0x3e16c740, v101
	v_cvt_pk_bf16_f32 v100, v100, v101
	v_mul_f32_e32 v102, 0x3e16c740, v102
	v_mul_f32_e32 v103, 0x3e16c740, v103
	v_cvt_pk_bf16_f32 v102, v102, v103
	v_mul_f32_e32 v104, 0x3e16c740, v104
	v_mul_f32_e32 v105, 0x3e16c740, v105
	v_cvt_pk_bf16_f32 v104, v104, v105
	v_mul_f32_e32 v106, 0x3e16c740, v106
	v_mul_f32_e32 v107, 0x3e16c740, v107
	v_cvt_pk_bf16_f32 v106, v106, v107
	v_mul_f32_e32 v108, 0x3e16c740, v108
	v_mul_f32_e32 v109, 0x3e16c740, v109
	v_cvt_pk_bf16_f32 v108, v108, v109
	v_mul_f32_e32 v110, 0x3e16c740, v110
	v_mul_f32_e32 v111, 0x3e16c740, v111
	v_cvt_pk_bf16_f32 v110, v110, v111
	s_mov_b32 s4, s70
	s_mov_b32 s5, s71
	global_store_short v145, v96, s[4:5] offset:64
	s_add_u32 s4, s4, 0x300
	s_addc_u32 s5, s5, 0
	global_store_short_d16_hi v145, v96, s[4:5] offset:64
	s_add_u32 s4, s70, 0x600
	s_addc_u32 s5, s71, 0
	global_store_short v145, v98, s[4:5] offset:64
	s_add_u32 s4, s4, 0x300
	s_addc_u32 s5, s5, 0
	global_store_short_d16_hi v145, v98, s[4:5] offset:64
	s_add_u32 s4, s70, 0x1800
	s_addc_u32 s5, s71, 0
	global_store_short v145, v100, s[4:5] offset:64
	s_add_u32 s4, s4, 0x300
	s_addc_u32 s5, s5, 0
	global_store_short_d16_hi v145, v100, s[4:5] offset:64
	s_add_u32 s4, s70, 0x1e00
	s_addc_u32 s5, s71, 0
	global_store_short v145, v102, s[4:5] offset:64
	s_add_u32 s4, s4, 0x300
	s_addc_u32 s5, s5, 0
	global_store_short_d16_hi v145, v102, s[4:5] offset:64
	s_add_u32 s4, s70, 0x3000
	s_addc_u32 s5, s71, 0
	global_store_short v145, v104, s[4:5] offset:64
	s_add_u32 s4, s4, 0x300
	s_addc_u32 s5, s5, 0
	global_store_short_d16_hi v145, v104, s[4:5] offset:64
	s_add_u32 s4, s70, 0x3600
	s_addc_u32 s5, s71, 0
	global_store_short v145, v106, s[4:5] offset:64
	s_add_u32 s4, s4, 0x300
	s_addc_u32 s5, s5, 0
	global_store_short_d16_hi v145, v106, s[4:5] offset:64
	s_add_u32 s4, s70, 0x4800
	s_addc_u32 s5, s71, 0
	global_store_short v145, v108, s[4:5] offset:64
	s_add_u32 s4, s4, 0x300
	s_addc_u32 s5, s5, 0
	global_store_short_d16_hi v145, v108, s[4:5] offset:64
	s_add_u32 s4, s70, 0x4e00
	s_addc_u32 s5, s71, 0
	global_store_short v145, v110, s[4:5] offset:64
	s_add_u32 s4, s4, 0x300
	s_addc_u32 s5, s5, 0
	global_store_short_d16_hi v145, v110, s[4:5] offset:64
	v_mul_f32_e32 v64, 0x3e16c740, v64
	v_mul_f32_e32 v65, 0x3e16c740, v65
	v_cvt_pk_bf16_f32 v64, v64, v65
	v_mul_f32_e32 v66, 0x3e16c740, v66
	v_mul_f32_e32 v67, 0x3e16c740, v67
	v_cvt_pk_bf16_f32 v66, v66, v67
	v_mul_f32_e32 v68, 0x3e16c740, v68
	v_mul_f32_e32 v69, 0x3e16c740, v69
	v_cvt_pk_bf16_f32 v68, v68, v69
	v_mul_f32_e32 v70, 0x3e16c740, v70
	v_mul_f32_e32 v71, 0x3e16c740, v71
	v_cvt_pk_bf16_f32 v70, v70, v71
	v_mul_f32_e32 v72, 0x3e16c740, v72
	v_mul_f32_e32 v73, 0x3e16c740, v73
	v_cvt_pk_bf16_f32 v72, v72, v73
	v_mul_f32_e32 v74, 0x3e16c740, v74
	v_mul_f32_e32 v75, 0x3e16c740, v75
	v_cvt_pk_bf16_f32 v74, v74, v75
	v_mul_f32_e32 v76, 0x3e16c740, v76
	v_mul_f32_e32 v77, 0x3e16c740, v77
	v_cvt_pk_bf16_f32 v76, v76, v77
	v_mul_f32_e32 v78, 0x3e16c740, v78
	v_mul_f32_e32 v79, 0x3e16c740, v79
	v_cvt_pk_bf16_f32 v78, v78, v79
	s_add_u32 s4, s70, 0x6000
	s_addc_u32 s5, s71, 0
	global_store_short v145, v64, s[4:5] offset:64
	s_add_u32 s4, s4, 0x300
	s_addc_u32 s5, s5, 0
	global_store_short_d16_hi v145, v64, s[4:5] offset:64
	s_add_u32 s4, s70, 0x6600
	s_addc_u32 s5, s71, 0
	global_store_short v145, v66, s[4:5] offset:64
	s_add_u32 s4, s4, 0x300
	s_addc_u32 s5, s5, 0
	global_store_short_d16_hi v145, v66, s[4:5] offset:64
	s_add_u32 s4, s70, 0x7800
	s_addc_u32 s5, s71, 0
	global_store_short v145, v68, s[4:5] offset:64
	s_add_u32 s4, s4, 0x300
	s_addc_u32 s5, s5, 0
	global_store_short_d16_hi v145, v68, s[4:5] offset:64
	s_add_u32 s4, s70, 0x7e00
	s_addc_u32 s5, s71, 0
	global_store_short v145, v70, s[4:5] offset:64
	s_add_u32 s4, s4, 0x300
	s_addc_u32 s5, s5, 0
	global_store_short_d16_hi v145, v70, s[4:5] offset:64
	s_add_u32 s4, s70, 0x9000
	s_addc_u32 s5, s71, 0
	global_store_short v145, v72, s[4:5] offset:64
	s_add_u32 s4, s4, 0x300
	s_addc_u32 s5, s5, 0
	global_store_short_d16_hi v145, v72, s[4:5] offset:64
	s_add_u32 s4, s70, 0x9600
	s_addc_u32 s5, s71, 0
	global_store_short v145, v74, s[4:5] offset:64
	s_add_u32 s4, s4, 0x300
	s_addc_u32 s5, s5, 0
	global_store_short_d16_hi v145, v74, s[4:5] offset:64
	s_add_u32 s4, s70, 0xa800
	s_addc_u32 s5, s71, 0
	global_store_short v145, v76, s[4:5] offset:64
	s_add_u32 s4, s4, 0x300
	s_addc_u32 s5, s5, 0
	global_store_short_d16_hi v145, v76, s[4:5] offset:64
	s_add_u32 s4, s70, 0xae00
	s_addc_u32 s5, s71, 0
	global_store_short v145, v78, s[4:5] offset:64
	s_add_u32 s4, s4, 0x300
	s_addc_u32 s5, s5, 0
	global_store_short_d16_hi v145, v78, s[4:5] offset:64
	v_mul_f32_e32 v32, 0x3e16c740, v32
	v_mul_f32_e32 v33, 0x3e16c740, v33
	v_cvt_pk_bf16_f32 v32, v32, v33
	v_mul_f32_e32 v34, 0x3e16c740, v34
	v_mul_f32_e32 v35, 0x3e16c740, v35
	v_cvt_pk_bf16_f32 v34, v34, v35
	v_mul_f32_e32 v36, 0x3e16c740, v36
	v_mul_f32_e32 v37, 0x3e16c740, v37
	v_cvt_pk_bf16_f32 v36, v36, v37
	v_mul_f32_e32 v38, 0x3e16c740, v38
	v_mul_f32_e32 v39, 0x3e16c740, v39
	v_cvt_pk_bf16_f32 v38, v38, v39
	v_mul_f32_e32 v40, 0x3e16c740, v40
	v_mul_f32_e32 v41, 0x3e16c740, v41
	v_cvt_pk_bf16_f32 v40, v40, v41
	v_mul_f32_e32 v42, 0x3e16c740, v42
	v_mul_f32_e32 v43, 0x3e16c740, v43
	v_cvt_pk_bf16_f32 v42, v42, v43
	v_mul_f32_e32 v44, 0x3e16c740, v44
	v_mul_f32_e32 v45, 0x3e16c740, v45
	v_cvt_pk_bf16_f32 v44, v44, v45
	v_mul_f32_e32 v46, 0x3e16c740, v46
	v_mul_f32_e32 v47, 0x3e16c740, v47
	v_cvt_pk_bf16_f32 v46, v46, v47
	s_add_u32 s4, s70, 0xc000
	s_addc_u32 s5, s71, 0
	global_store_short v145, v32, s[4:5] offset:64
	s_add_u32 s4, s4, 0x300
	s_addc_u32 s5, s5, 0
	global_store_short_d16_hi v145, v32, s[4:5] offset:64
	s_add_u32 s4, s70, 0xc600
	s_addc_u32 s5, s71, 0
	global_store_short v145, v34, s[4:5] offset:64
	s_add_u32 s4, s4, 0x300
	s_addc_u32 s5, s5, 0
	global_store_short_d16_hi v145, v34, s[4:5] offset:64
	s_add_u32 s4, s70, 0xd800
	s_addc_u32 s5, s71, 0
	global_store_short v145, v36, s[4:5] offset:64
	s_add_u32 s4, s4, 0x300
	s_addc_u32 s5, s5, 0
	global_store_short_d16_hi v145, v36, s[4:5] offset:64
	s_add_u32 s4, s70, 0xde00
	s_addc_u32 s5, s71, 0
	global_store_short v145, v38, s[4:5] offset:64
	s_add_u32 s4, s4, 0x300
	s_addc_u32 s5, s5, 0
	global_store_short_d16_hi v145, v38, s[4:5] offset:64
	s_add_u32 s4, s70, 0xf000
	s_addc_u32 s5, s71, 0
	global_store_short v145, v40, s[4:5] offset:64
	s_add_u32 s4, s4, 0x300
	s_addc_u32 s5, s5, 0
	global_store_short_d16_hi v145, v40, s[4:5] offset:64
	s_add_u32 s4, s70, 0xf600
	s_addc_u32 s5, s71, 0
	global_store_short v145, v42, s[4:5] offset:64
	s_add_u32 s4, s4, 0x300
	s_addc_u32 s5, s5, 0
	global_store_short_d16_hi v145, v42, s[4:5] offset:64
	s_add_u32 s4, s70, 0x10800
	s_addc_u32 s5, s71, 0
	global_store_short v145, v44, s[4:5] offset:64
	s_add_u32 s4, s4, 0x300
	s_addc_u32 s5, s5, 0
	global_store_short_d16_hi v145, v44, s[4:5] offset:64
	s_add_u32 s4, s70, 0x10e00
	s_addc_u32 s5, s71, 0
	global_store_short v145, v46, s[4:5] offset:64
	s_add_u32 s4, s4, 0x300
	s_addc_u32 s5, s5, 0
	global_store_short_d16_hi v145, v46, s[4:5] offset:64
	v_mul_f32_e32 v0, 0x3e16c740, v0
	v_mul_f32_e32 v1, 0x3e16c740, v1
	v_cvt_pk_bf16_f32 v0, v0, v1
	v_mul_f32_e32 v2, 0x3e16c740, v2
	v_mul_f32_e32 v3, 0x3e16c740, v3
	v_cvt_pk_bf16_f32 v2, v2, v3
	v_mul_f32_e32 v4, 0x3e16c740, v4
	v_mul_f32_e32 v5, 0x3e16c740, v5
	v_cvt_pk_bf16_f32 v4, v4, v5
	v_mul_f32_e32 v6, 0x3e16c740, v6
	v_mul_f32_e32 v7, 0x3e16c740, v7
	v_cvt_pk_bf16_f32 v6, v6, v7
	v_mul_f32_e32 v8, 0x3e16c740, v8
	v_mul_f32_e32 v9, 0x3e16c740, v9
	v_cvt_pk_bf16_f32 v8, v8, v9
	v_mul_f32_e32 v10, 0x3e16c740, v10
	v_mul_f32_e32 v11, 0x3e16c740, v11
	v_cvt_pk_bf16_f32 v10, v10, v11
	v_mul_f32_e32 v12, 0x3e16c740, v12
	v_mul_f32_e32 v13, 0x3e16c740, v13
	v_cvt_pk_bf16_f32 v12, v12, v13
	v_mul_f32_e32 v14, 0x3e16c740, v14
	v_mul_f32_e32 v15, 0x3e16c740, v15
	v_cvt_pk_bf16_f32 v14, v14, v15
	s_add_u32 s4, s70, 0x12000
	s_addc_u32 s5, s71, 0
	global_store_short v145, v0, s[4:5] offset:64
	s_add_u32 s4, s4, 0x300
	s_addc_u32 s5, s5, 0
	global_store_short_d16_hi v145, v0, s[4:5] offset:64
	s_add_u32 s4, s70, 0x12600
	s_addc_u32 s5, s71, 0
	global_store_short v145, v2, s[4:5] offset:64
	s_add_u32 s4, s4, 0x300
	s_addc_u32 s5, s5, 0
	global_store_short_d16_hi v145, v2, s[4:5] offset:64
	s_add_u32 s4, s70, 0x13800
	s_addc_u32 s5, s71, 0
	global_store_short v145, v4, s[4:5] offset:64
	s_add_u32 s4, s4, 0x300
	s_addc_u32 s5, s5, 0
	global_store_short_d16_hi v145, v4, s[4:5] offset:64
	s_add_u32 s4, s70, 0x13e00
	s_addc_u32 s5, s71, 0
	global_store_short v145, v6, s[4:5] offset:64
	s_add_u32 s4, s4, 0x300
	s_addc_u32 s5, s5, 0
	global_store_short_d16_hi v145, v6, s[4:5] offset:64
	s_add_u32 s4, s70, 0x15000
	s_addc_u32 s5, s71, 0
	global_store_short v145, v8, s[4:5] offset:64
	s_add_u32 s4, s4, 0x300
	s_addc_u32 s5, s5, 0
	global_store_short_d16_hi v145, v8, s[4:5] offset:64
	s_add_u32 s4, s70, 0x15600
	s_addc_u32 s5, s71, 0
	global_store_short v145, v10, s[4:5] offset:64
	s_add_u32 s4, s4, 0x300
	s_addc_u32 s5, s5, 0
	global_store_short_d16_hi v145, v10, s[4:5] offset:64
	s_add_u32 s4, s70, 0x16800
	s_addc_u32 s5, s71, 0
	global_store_short v145, v12, s[4:5] offset:64
	s_add_u32 s4, s4, 0x300
	s_addc_u32 s5, s5, 0
	global_store_short_d16_hi v145, v12, s[4:5] offset:64
	s_add_u32 s4, s70, 0x16e00
	s_addc_u32 s5, s71, 0
	global_store_short v145, v14, s[4:5] offset:64
	s_add_u32 s4, s4, 0x300
	s_addc_u32 s5, s5, 0
	global_store_short_d16_hi v145, v14, s[4:5] offset:64
	s_lshr_b32 s6, s55, 6
	v_lshrrev_b32_e32 v128, 6, v178
	v_add_u32_e32 v128, s6, v128
	v_lshlrev_b32_e32 v133, 3, v177
	v_and_b32_e32 v130, 15, v128
	v_lshl_or_b32 v130, v130, 6, v133
	v_add_u32_e32 v131, 1, v128
	v_and_b32_e32 v131, 15, v131
	v_lshl_or_b32 v131, v131, 6, v133
	v_and_b32_e32 v146, 4, v178
	v_lshl_or_b32 v146, v146, 6, v133
	v_cndmask_b32_e64 v130, v130, v146, s[38:39]
	v_cndmask_b32_e64 v131, v131, v146, s[38:39]
	v_add_u32_e32 v130, 0x20000, v130
	v_add_u32_e32 v131, 0x20000, v131
	v_cndmask_b32_e64 v132, 0, 64, s[38:39]
	v_mad_u32_u24 v128, v132, 0, v130
	ds_read_b64 v[96:97], v128
	v_mad_u32_u24 v128, v132, 1, v130
	ds_read_b64 v[98:99], v128
	v_mad_u32_u24 v128, v132, 2, v130
	ds_read_b64 v[100:101], v128
	v_mad_u32_u24 v128, v132, 3, v130
	ds_read_b64 v[102:103], v128
	v_mad_u32_u24 v128, v132, 8, v130
	ds_read_b64 v[104:105], v128
	v_mad_u32_u24 v128, v132, 9, v130
	ds_read_b64 v[106:107], v128
	v_mad_u32_u24 v128, v132, 10, v130
	ds_read_b64 v[108:109], v128
	v_mad_u32_u24 v128, v132, 11, v130
	ds_read_b64 v[110:111], v128
	v_mad_u32_u24 v128, v132, 16, v130
	ds_read_b64 v[64:65], v128
	v_mad_u32_u24 v128, v132, 17, v130
	ds_read_b64 v[66:67], v128
	v_mad_u32_u24 v128, v132, 18, v130
	ds_read_b64 v[68:69], v128
	v_mad_u32_u24 v128, v132, 19, v130
	ds_read_b64 v[70:71], v128
	v_mad_u32_u24 v128, v132, 24, v130
	ds_read_b64 v[72:73], v128
	v_mad_u32_u24 v128, v132, 25, v130
	ds_read_b64 v[74:75], v128
	v_mad_u32_u24 v128, v132, 26, v130
	ds_read_b64 v[76:77], v128
	v_mad_u32_u24 v128, v132, 27, v130
	ds_read_b64 v[78:79], v128
	v_mov_b32_dpp v32, v112 row_ror:8 row_mask:0xf bank_mask:0xf
	v_mov_b32_dpp v33, v113 row_ror:8 row_mask:0xf bank_mask:0xf
	v_mov_b32_dpp v34, v114 row_ror:8 row_mask:0xf bank_mask:0xf
	v_mov_b32_dpp v35, v115 row_ror:8 row_mask:0xf bank_mask:0xf
	v_mov_b32_dpp v36, v116 row_ror:8 row_mask:0xf bank_mask:0xf
	v_mov_b32_dpp v37, v117 row_ror:8 row_mask:0xf bank_mask:0xf
	v_mov_b32_dpp v38, v118 row_ror:8 row_mask:0xf bank_mask:0xf
	v_mov_b32_dpp v39, v119 row_ror:8 row_mask:0xf bank_mask:0xf
	v_mov_b32_dpp v40, v120 row_ror:8 row_mask:0xf bank_mask:0xf
	v_mov_b32_dpp v41, v121 row_ror:8 row_mask:0xf bank_mask:0xf
	v_mov_b32_dpp v42, v122 row_ror:8 row_mask:0xf bank_mask:0xf
	v_mov_b32_dpp v43, v123 row_ror:8 row_mask:0xf bank_mask:0xf
	v_mov_b32_dpp v44, v124 row_ror:8 row_mask:0xf bank_mask:0xf
	v_mov_b32_dpp v45, v125 row_ror:8 row_mask:0xf bank_mask:0xf
	v_mov_b32_dpp v46, v126 row_ror:8 row_mask:0xf bank_mask:0xf
	v_mov_b32_dpp v47, v127 row_ror:8 row_mask:0xf bank_mask:0xf
	s_waitcnt lgkmcnt(0)
	v_cndmask_b32_e64 v32, v32, -v32, s[36:37]
	v_mul_f32_e32 v112, v112, v96
	v_mul_f32_e32 v32, v97, v32
	v_add_f32_e32 v112, v112, v32
	v_mul_f32_e32 v112, 0x3e16c740, v112
	v_cndmask_b32_e64 v33, v33, -v33, s[36:37]
	v_mul_f32_e32 v113, v113, v98
	v_mul_f32_e32 v33, v99, v33
	v_add_f32_e32 v113, v113, v33
	v_mul_f32_e32 v113, 0x3e16c740, v113
	v_cndmask_b32_e64 v34, v34, -v34, s[36:37]
	v_mul_f32_e32 v114, v114, v100
	v_mul_f32_e32 v34, v101, v34
	v_add_f32_e32 v114, v114, v34
	v_mul_f32_e32 v114, 0x3e16c740, v114
	v_cndmask_b32_e64 v35, v35, -v35, s[36:37]
	v_mul_f32_e32 v115, v115, v102
	v_mul_f32_e32 v35, v103, v35
	v_add_f32_e32 v115, v115, v35
	v_mul_f32_e32 v115, 0x3e16c740, v115
	v_cndmask_b32_e64 v36, v36, -v36, s[36:37]
	v_mul_f32_e32 v116, v116, v104
	v_mul_f32_e32 v36, v105, v36
	v_add_f32_e32 v116, v116, v36
	v_mul_f32_e32 v116, 0x3e16c740, v116
	v_cndmask_b32_e64 v37, v37, -v37, s[36:37]
	v_mul_f32_e32 v117, v117, v106
	v_mul_f32_e32 v37, v107, v37
	v_add_f32_e32 v117, v117, v37
	v_mul_f32_e32 v117, 0x3e16c740, v117
	v_cndmask_b32_e64 v38, v38, -v38, s[36:37]
	v_mul_f32_e32 v118, v118, v108
	v_mul_f32_e32 v38, v109, v38
	v_add_f32_e32 v118, v118, v38
	v_mul_f32_e32 v118, 0x3e16c740, v118
	v_cndmask_b32_e64 v39, v39, -v39, s[36:37]
	v_mul_f32_e32 v119, v119, v110
	v_mul_f32_e32 v39, v111, v39
	v_add_f32_e32 v119, v119, v39
	v_mul_f32_e32 v119, 0x3e16c740, v119
	v_cndmask_b32_e64 v40, v40, -v40, s[36:37]
	v_mul_f32_e32 v120, v120, v64
	v_mul_f32_e32 v40, v65, v40
	v_add_f32_e32 v120, v120, v40
	v_mul_f32_e32 v120, 0x3e16c740, v120
	v_cndmask_b32_e64 v41, v41, -v41, s[36:37]
	v_mul_f32_e32 v121, v121, v66
	v_mul_f32_e32 v41, v67, v41
	v_add_f32_e32 v121, v121, v41
	v_mul_f32_e32 v121, 0x3e16c740, v121
	v_cndmask_b32_e64 v42, v42, -v42, s[36:37]
	v_mul_f32_e32 v122, v122, v68
	v_mul_f32_e32 v42, v69, v42
	v_add_f32_e32 v122, v122, v42
	v_mul_f32_e32 v122, 0x3e16c740, v122
	v_cndmask_b32_e64 v43, v43, -v43, s[36:37]
	v_mul_f32_e32 v123, v123, v70
	v_mul_f32_e32 v43, v71, v43
	v_add_f32_e32 v123, v123, v43
	v_mul_f32_e32 v123, 0x3e16c740, v123
	v_cndmask_b32_e64 v44, v44, -v44, s[36:37]
	v_mul_f32_e32 v124, v124, v72
	v_mul_f32_e32 v44, v73, v44
	v_add_f32_e32 v124, v124, v44
	v_mul_f32_e32 v124, 0x3e16c740, v124
	v_cndmask_b32_e64 v45, v45, -v45, s[36:37]
	v_mul_f32_e32 v125, v125, v74
	v_mul_f32_e32 v45, v75, v45
	v_add_f32_e32 v125, v125, v45
	v_mul_f32_e32 v125, 0x3e16c740, v125
	v_cndmask_b32_e64 v46, v46, -v46, s[36:37]
	v_mul_f32_e32 v126, v126, v76
	v_mul_f32_e32 v46, v77, v46
	v_add_f32_e32 v126, v126, v46
	v_mul_f32_e32 v126, 0x3e16c740, v126
	v_cndmask_b32_e64 v47, v47, -v47, s[36:37]
	v_mul_f32_e32 v127, v127, v78
	v_mul_f32_e32 v47, v79, v47
	v_add_f32_e32 v127, v127, v47
	v_mul_f32_e32 v127, 0x3e16c740, v127
	v_cvt_pk_bf16_f32 v112, v112, v113
	v_cvt_pk_bf16_f32 v114, v114, v115
	v_cvt_pk_bf16_f32 v116, v116, v117
	v_cvt_pk_bf16_f32 v118, v118, v119
	v_cvt_pk_bf16_f32 v120, v120, v121
	v_cvt_pk_bf16_f32 v122, v122, v123
	v_cvt_pk_bf16_f32 v124, v124, v125
	v_cvt_pk_bf16_f32 v126, v126, v127
	s_mov_b32 s4, s70
	s_mov_b32 s5, s71
	global_store_short v145, v112, s[4:5]
	s_add_u32 s4, s4, 0x300
	s_addc_u32 s5, s5, 0
	global_store_short_d16_hi v145, v112, s[4:5]
	s_add_u32 s4, s70, 0x600
	s_addc_u32 s5, s71, 0
	global_store_short v145, v114, s[4:5]
	s_add_u32 s4, s4, 0x300
	s_addc_u32 s5, s5, 0
	global_store_short_d16_hi v145, v114, s[4:5]
	s_add_u32 s4, s70, 0x1800
	s_addc_u32 s5, s71, 0
	global_store_short v145, v116, s[4:5]
	s_add_u32 s4, s4, 0x300
	s_addc_u32 s5, s5, 0
	global_store_short_d16_hi v145, v116, s[4:5]
	s_add_u32 s4, s70, 0x1e00
	s_addc_u32 s5, s71, 0
	global_store_short v145, v118, s[4:5]
	s_add_u32 s4, s4, 0x300
	s_addc_u32 s5, s5, 0
	global_store_short_d16_hi v145, v118, s[4:5]
	s_add_u32 s4, s70, 0x3000
	s_addc_u32 s5, s71, 0
	global_store_short v145, v120, s[4:5]
	s_add_u32 s4, s4, 0x300
	s_addc_u32 s5, s5, 0
	global_store_short_d16_hi v145, v120, s[4:5]
	s_add_u32 s4, s70, 0x3600
	s_addc_u32 s5, s71, 0
	global_store_short v145, v122, s[4:5]
	s_add_u32 s4, s4, 0x300
	s_addc_u32 s5, s5, 0
	global_store_short_d16_hi v145, v122, s[4:5]
	s_add_u32 s4, s70, 0x4800
	s_addc_u32 s5, s71, 0
	global_store_short v145, v124, s[4:5]
	s_add_u32 s4, s4, 0x300
	s_addc_u32 s5, s5, 0
	global_store_short_d16_hi v145, v124, s[4:5]
	s_add_u32 s4, s70, 0x4e00
	s_addc_u32 s5, s71, 0
	global_store_short v145, v126, s[4:5]
	s_add_u32 s4, s4, 0x300
	s_addc_u32 s5, s5, 0
	global_store_short_d16_hi v145, v126, s[4:5]
	v_mad_u32_u24 v128, v132, 32, v130
	ds_read_b64 v[96:97], v128
	v_mad_u32_u24 v128, v132, 33, v130
	ds_read_b64 v[98:99], v128
	v_mad_u32_u24 v128, v132, 34, v130
	ds_read_b64 v[100:101], v128
	v_mad_u32_u24 v128, v132, 35, v130
	ds_read_b64 v[102:103], v128
	v_mad_u32_u24 v128, v132, 40, v130
	ds_read_b64 v[104:105], v128
	v_mad_u32_u24 v128, v132, 41, v130
	ds_read_b64 v[106:107], v128
	v_mad_u32_u24 v128, v132, 42, v130
	ds_read_b64 v[108:109], v128
	v_mad_u32_u24 v128, v132, 43, v130
	ds_read_b64 v[110:111], v128
	v_mad_u32_u24 v128, v132, 48, v130
	ds_read_b64 v[64:65], v128
	v_mad_u32_u24 v128, v132, 49, v130
	ds_read_b64 v[66:67], v128
	v_mad_u32_u24 v128, v132, 50, v130
	ds_read_b64 v[68:69], v128
	v_mad_u32_u24 v128, v132, 51, v130
	ds_read_b64 v[70:71], v128
	v_mad_u32_u24 v128, v132, 56, v130
	ds_read_b64 v[72:73], v128
	v_mad_u32_u24 v128, v132, 57, v130
	ds_read_b64 v[74:75], v128
	v_mad_u32_u24 v128, v132, 58, v130
	ds_read_b64 v[76:77], v128
	v_mad_u32_u24 v128, v132, 59, v130
	ds_read_b64 v[78:79], v128
	v_mov_b32_dpp v32, v80 row_ror:8 row_mask:0xf bank_mask:0xf
	v_mov_b32_dpp v33, v81 row_ror:8 row_mask:0xf bank_mask:0xf
	v_mov_b32_dpp v34, v82 row_ror:8 row_mask:0xf bank_mask:0xf
	v_mov_b32_dpp v35, v83 row_ror:8 row_mask:0xf bank_mask:0xf
	v_mov_b32_dpp v36, v84 row_ror:8 row_mask:0xf bank_mask:0xf
	v_mov_b32_dpp v37, v85 row_ror:8 row_mask:0xf bank_mask:0xf
	v_mov_b32_dpp v38, v86 row_ror:8 row_mask:0xf bank_mask:0xf
	v_mov_b32_dpp v39, v87 row_ror:8 row_mask:0xf bank_mask:0xf
	v_mov_b32_dpp v40, v88 row_ror:8 row_mask:0xf bank_mask:0xf
	v_mov_b32_dpp v41, v89 row_ror:8 row_mask:0xf bank_mask:0xf
	v_mov_b32_dpp v42, v90 row_ror:8 row_mask:0xf bank_mask:0xf
	v_mov_b32_dpp v43, v91 row_ror:8 row_mask:0xf bank_mask:0xf
	v_mov_b32_dpp v44, v92 row_ror:8 row_mask:0xf bank_mask:0xf
	v_mov_b32_dpp v45, v93 row_ror:8 row_mask:0xf bank_mask:0xf
	v_mov_b32_dpp v46, v94 row_ror:8 row_mask:0xf bank_mask:0xf
	v_mov_b32_dpp v47, v95 row_ror:8 row_mask:0xf bank_mask:0xf
	s_waitcnt lgkmcnt(0)
	v_cndmask_b32_e64 v32, v32, -v32, s[36:37]
	v_mul_f32_e32 v80, v80, v96
	v_mul_f32_e32 v32, v97, v32
	v_add_f32_e32 v80, v80, v32
	v_mul_f32_e32 v80, 0x3e16c740, v80
	v_cndmask_b32_e64 v33, v33, -v33, s[36:37]
	v_mul_f32_e32 v81, v81, v98
	v_mul_f32_e32 v33, v99, v33
	v_add_f32_e32 v81, v81, v33
	v_mul_f32_e32 v81, 0x3e16c740, v81
	v_cndmask_b32_e64 v34, v34, -v34, s[36:37]
	v_mul_f32_e32 v82, v82, v100
	v_mul_f32_e32 v34, v101, v34
	v_add_f32_e32 v82, v82, v34
	v_mul_f32_e32 v82, 0x3e16c740, v82
	v_cndmask_b32_e64 v35, v35, -v35, s[36:37]
	v_mul_f32_e32 v83, v83, v102
	v_mul_f32_e32 v35, v103, v35
	v_add_f32_e32 v83, v83, v35
	v_mul_f32_e32 v83, 0x3e16c740, v83
	v_cndmask_b32_e64 v36, v36, -v36, s[36:37]
	v_mul_f32_e32 v84, v84, v104
	v_mul_f32_e32 v36, v105, v36
	v_add_f32_e32 v84, v84, v36
	v_mul_f32_e32 v84, 0x3e16c740, v84
	v_cndmask_b32_e64 v37, v37, -v37, s[36:37]
	v_mul_f32_e32 v85, v85, v106
	v_mul_f32_e32 v37, v107, v37
	v_add_f32_e32 v85, v85, v37
	v_mul_f32_e32 v85, 0x3e16c740, v85
	v_cndmask_b32_e64 v38, v38, -v38, s[36:37]
	v_mul_f32_e32 v86, v86, v108
	v_mul_f32_e32 v38, v109, v38
	v_add_f32_e32 v86, v86, v38
	v_mul_f32_e32 v86, 0x3e16c740, v86
	v_cndmask_b32_e64 v39, v39, -v39, s[36:37]
	v_mul_f32_e32 v87, v87, v110
	v_mul_f32_e32 v39, v111, v39
	v_add_f32_e32 v87, v87, v39
	v_mul_f32_e32 v87, 0x3e16c740, v87
	v_cndmask_b32_e64 v40, v40, -v40, s[36:37]
	v_mul_f32_e32 v88, v88, v64
	v_mul_f32_e32 v40, v65, v40
	v_add_f32_e32 v88, v88, v40
	v_mul_f32_e32 v88, 0x3e16c740, v88
	v_cndmask_b32_e64 v41, v41, -v41, s[36:37]
	v_mul_f32_e32 v89, v89, v66
	v_mul_f32_e32 v41, v67, v41
	v_add_f32_e32 v89, v89, v41
	v_mul_f32_e32 v89, 0x3e16c740, v89
	v_cndmask_b32_e64 v42, v42, -v42, s[36:37]
	v_mul_f32_e32 v90, v90, v68
	v_mul_f32_e32 v42, v69, v42
	v_add_f32_e32 v90, v90, v42
	v_mul_f32_e32 v90, 0x3e16c740, v90
	v_cndmask_b32_e64 v43, v43, -v43, s[36:37]
	v_mul_f32_e32 v91, v91, v70
	v_mul_f32_e32 v43, v71, v43
	v_add_f32_e32 v91, v91, v43
	v_mul_f32_e32 v91, 0x3e16c740, v91
	v_cndmask_b32_e64 v44, v44, -v44, s[36:37]
	v_mul_f32_e32 v92, v92, v72
	v_mul_f32_e32 v44, v73, v44
	v_add_f32_e32 v92, v92, v44
	v_mul_f32_e32 v92, 0x3e16c740, v92
	v_cndmask_b32_e64 v45, v45, -v45, s[36:37]
	v_mul_f32_e32 v93, v93, v74
	v_mul_f32_e32 v45, v75, v45
	v_add_f32_e32 v93, v93, v45
	v_mul_f32_e32 v93, 0x3e16c740, v93
	v_cndmask_b32_e64 v46, v46, -v46, s[36:37]
	v_mul_f32_e32 v94, v94, v76
	v_mul_f32_e32 v46, v77, v46
	v_add_f32_e32 v94, v94, v46
	v_mul_f32_e32 v94, 0x3e16c740, v94
	v_cndmask_b32_e64 v47, v47, -v47, s[36:37]
	v_mul_f32_e32 v95, v95, v78
	v_mul_f32_e32 v47, v79, v47
	v_add_f32_e32 v95, v95, v47
	v_mul_f32_e32 v95, 0x3e16c740, v95
	v_cvt_pk_bf16_f32 v80, v80, v81
	v_cvt_pk_bf16_f32 v82, v82, v83
	v_cvt_pk_bf16_f32 v84, v84, v85
	v_cvt_pk_bf16_f32 v86, v86, v87
	v_cvt_pk_bf16_f32 v88, v88, v89
	v_cvt_pk_bf16_f32 v90, v90, v91
	v_cvt_pk_bf16_f32 v92, v92, v93
	v_cvt_pk_bf16_f32 v94, v94, v95
	s_add_u32 s4, s70, 0x6000
	s_addc_u32 s5, s71, 0
	global_store_short v145, v80, s[4:5]
	s_add_u32 s4, s4, 0x300
	s_addc_u32 s5, s5, 0
	global_store_short_d16_hi v145, v80, s[4:5]
	s_add_u32 s4, s70, 0x6600
	s_addc_u32 s5, s71, 0
	global_store_short v145, v82, s[4:5]
	s_add_u32 s4, s4, 0x300
	s_addc_u32 s5, s5, 0
	global_store_short_d16_hi v145, v82, s[4:5]
	s_add_u32 s4, s70, 0x7800
	s_addc_u32 s5, s71, 0
	global_store_short v145, v84, s[4:5]
	s_add_u32 s4, s4, 0x300
	s_addc_u32 s5, s5, 0
	global_store_short_d16_hi v145, v84, s[4:5]
	s_add_u32 s4, s70, 0x7e00
	s_addc_u32 s5, s71, 0
	global_store_short v145, v86, s[4:5]
	s_add_u32 s4, s4, 0x300
	s_addc_u32 s5, s5, 0
	global_store_short_d16_hi v145, v86, s[4:5]
	s_add_u32 s4, s70, 0x9000
	s_addc_u32 s5, s71, 0
	global_store_short v145, v88, s[4:5]
	s_add_u32 s4, s4, 0x300
	s_addc_u32 s5, s5, 0
	global_store_short_d16_hi v145, v88, s[4:5]
	s_add_u32 s4, s70, 0x9600
	s_addc_u32 s5, s71, 0
	global_store_short v145, v90, s[4:5]
	s_add_u32 s4, s4, 0x300
	s_addc_u32 s5, s5, 0
	global_store_short_d16_hi v145, v90, s[4:5]
	s_add_u32 s4, s70, 0xa800
	s_addc_u32 s5, s71, 0
	global_store_short v145, v92, s[4:5]
	s_add_u32 s4, s4, 0x300
	s_addc_u32 s5, s5, 0
	global_store_short_d16_hi v145, v92, s[4:5]
	s_add_u32 s4, s70, 0xae00
	s_addc_u32 s5, s71, 0
	global_store_short v145, v94, s[4:5]
	s_add_u32 s4, s4, 0x300
	s_addc_u32 s5, s5, 0
	global_store_short_d16_hi v145, v94, s[4:5]
	v_mad_u32_u24 v128, v132, 0, v131
	ds_read_b64 v[96:97], v128
	v_mad_u32_u24 v128, v132, 1, v131
	ds_read_b64 v[98:99], v128
	v_mad_u32_u24 v128, v132, 2, v131
	ds_read_b64 v[100:101], v128
	v_mad_u32_u24 v128, v132, 3, v131
	ds_read_b64 v[102:103], v128
	v_mad_u32_u24 v128, v132, 8, v131
	ds_read_b64 v[104:105], v128
	v_mad_u32_u24 v128, v132, 9, v131
	ds_read_b64 v[106:107], v128
	v_mad_u32_u24 v128, v132, 10, v131
	ds_read_b64 v[108:109], v128
	v_mad_u32_u24 v128, v132, 11, v131
	ds_read_b64 v[110:111], v128
	v_mad_u32_u24 v128, v132, 16, v131
	ds_read_b64 v[64:65], v128
	v_mad_u32_u24 v128, v132, 17, v131
	ds_read_b64 v[66:67], v128
	v_mad_u32_u24 v128, v132, 18, v131
	ds_read_b64 v[68:69], v128
	v_mad_u32_u24 v128, v132, 19, v131
	ds_read_b64 v[70:71], v128
	v_mad_u32_u24 v128, v132, 24, v131
	ds_read_b64 v[72:73], v128
	v_mad_u32_u24 v128, v132, 25, v131
	ds_read_b64 v[74:75], v128
	v_mad_u32_u24 v128, v132, 26, v131
	ds_read_b64 v[76:77], v128
	v_mad_u32_u24 v128, v132, 27, v131
	ds_read_b64 v[78:79], v128
	v_mov_b32_dpp v32, v48 row_ror:8 row_mask:0xf bank_mask:0xf
	v_mov_b32_dpp v33, v49 row_ror:8 row_mask:0xf bank_mask:0xf
	v_mov_b32_dpp v34, v50 row_ror:8 row_mask:0xf bank_mask:0xf
	v_mov_b32_dpp v35, v51 row_ror:8 row_mask:0xf bank_mask:0xf
	v_mov_b32_dpp v36, v52 row_ror:8 row_mask:0xf bank_mask:0xf
	v_mov_b32_dpp v37, v53 row_ror:8 row_mask:0xf bank_mask:0xf
	v_mov_b32_dpp v38, v54 row_ror:8 row_mask:0xf bank_mask:0xf
	v_mov_b32_dpp v39, v55 row_ror:8 row_mask:0xf bank_mask:0xf
	v_mov_b32_dpp v40, v56 row_ror:8 row_mask:0xf bank_mask:0xf
	v_mov_b32_dpp v41, v57 row_ror:8 row_mask:0xf bank_mask:0xf
	v_mov_b32_dpp v42, v58 row_ror:8 row_mask:0xf bank_mask:0xf
	v_mov_b32_dpp v43, v59 row_ror:8 row_mask:0xf bank_mask:0xf
	v_mov_b32_dpp v44, v60 row_ror:8 row_mask:0xf bank_mask:0xf
	v_mov_b32_dpp v45, v61 row_ror:8 row_mask:0xf bank_mask:0xf
	v_mov_b32_dpp v46, v62 row_ror:8 row_mask:0xf bank_mask:0xf
	v_mov_b32_dpp v47, v63 row_ror:8 row_mask:0xf bank_mask:0xf
	s_waitcnt lgkmcnt(0)
	v_cndmask_b32_e64 v32, v32, -v32, s[36:37]
	v_mul_f32_e32 v48, v48, v96
	v_mul_f32_e32 v32, v97, v32
	v_add_f32_e32 v48, v48, v32
	v_mul_f32_e32 v48, 0x3e16c740, v48
	v_cndmask_b32_e64 v33, v33, -v33, s[36:37]
	v_mul_f32_e32 v49, v49, v98
	v_mul_f32_e32 v33, v99, v33
	v_add_f32_e32 v49, v49, v33
	v_mul_f32_e32 v49, 0x3e16c740, v49
	v_cndmask_b32_e64 v34, v34, -v34, s[36:37]
	v_mul_f32_e32 v50, v50, v100
	v_mul_f32_e32 v34, v101, v34
	v_add_f32_e32 v50, v50, v34
	v_mul_f32_e32 v50, 0x3e16c740, v50
	v_cndmask_b32_e64 v35, v35, -v35, s[36:37]
	v_mul_f32_e32 v51, v51, v102
	v_mul_f32_e32 v35, v103, v35
	v_add_f32_e32 v51, v51, v35
	v_mul_f32_e32 v51, 0x3e16c740, v51
	v_cndmask_b32_e64 v36, v36, -v36, s[36:37]
	v_mul_f32_e32 v52, v52, v104
	v_mul_f32_e32 v36, v105, v36
	v_add_f32_e32 v52, v52, v36
	v_mul_f32_e32 v52, 0x3e16c740, v52
	v_cndmask_b32_e64 v37, v37, -v37, s[36:37]
	v_mul_f32_e32 v53, v53, v106
	v_mul_f32_e32 v37, v107, v37
	v_add_f32_e32 v53, v53, v37
	v_mul_f32_e32 v53, 0x3e16c740, v53
	v_cndmask_b32_e64 v38, v38, -v38, s[36:37]
	v_mul_f32_e32 v54, v54, v108
	v_mul_f32_e32 v38, v109, v38
	v_add_f32_e32 v54, v54, v38
	v_mul_f32_e32 v54, 0x3e16c740, v54
	v_cndmask_b32_e64 v39, v39, -v39, s[36:37]
	v_mul_f32_e32 v55, v55, v110
	v_mul_f32_e32 v39, v111, v39
	v_add_f32_e32 v55, v55, v39
	v_mul_f32_e32 v55, 0x3e16c740, v55
	v_cndmask_b32_e64 v40, v40, -v40, s[36:37]
	v_mul_f32_e32 v56, v56, v64
	v_mul_f32_e32 v40, v65, v40
	v_add_f32_e32 v56, v56, v40
	v_mul_f32_e32 v56, 0x3e16c740, v56
	v_cndmask_b32_e64 v41, v41, -v41, s[36:37]
	v_mul_f32_e32 v57, v57, v66
	v_mul_f32_e32 v41, v67, v41
	v_add_f32_e32 v57, v57, v41
	v_mul_f32_e32 v57, 0x3e16c740, v57
	v_cndmask_b32_e64 v42, v42, -v42, s[36:37]
	v_mul_f32_e32 v58, v58, v68
	v_mul_f32_e32 v42, v69, v42
	v_add_f32_e32 v58, v58, v42
	v_mul_f32_e32 v58, 0x3e16c740, v58
	v_cndmask_b32_e64 v43, v43, -v43, s[36:37]
	v_mul_f32_e32 v59, v59, v70
	v_mul_f32_e32 v43, v71, v43
	v_add_f32_e32 v59, v59, v43
	v_mul_f32_e32 v59, 0x3e16c740, v59
	v_cndmask_b32_e64 v44, v44, -v44, s[36:37]
	v_mul_f32_e32 v60, v60, v72
	v_mul_f32_e32 v44, v73, v44
	v_add_f32_e32 v60, v60, v44
	v_mul_f32_e32 v60, 0x3e16c740, v60
	v_cndmask_b32_e64 v45, v45, -v45, s[36:37]
	v_mul_f32_e32 v61, v61, v74
	v_mul_f32_e32 v45, v75, v45
	v_add_f32_e32 v61, v61, v45
	v_mul_f32_e32 v61, 0x3e16c740, v61
	v_cndmask_b32_e64 v46, v46, -v46, s[36:37]
	v_mul_f32_e32 v62, v62, v76
	v_mul_f32_e32 v46, v77, v46
	v_add_f32_e32 v62, v62, v46
	v_mul_f32_e32 v62, 0x3e16c740, v62
	v_cndmask_b32_e64 v47, v47, -v47, s[36:37]
	v_mul_f32_e32 v63, v63, v78
	v_mul_f32_e32 v47, v79, v47
	v_add_f32_e32 v63, v63, v47
	v_mul_f32_e32 v63, 0x3e16c740, v63
	v_cvt_pk_bf16_f32 v48, v48, v49
	v_cvt_pk_bf16_f32 v50, v50, v51
	v_cvt_pk_bf16_f32 v52, v52, v53
	v_cvt_pk_bf16_f32 v54, v54, v55
	v_cvt_pk_bf16_f32 v56, v56, v57
	v_cvt_pk_bf16_f32 v58, v58, v59
	v_cvt_pk_bf16_f32 v60, v60, v61
	v_cvt_pk_bf16_f32 v62, v62, v63
	s_add_u32 s4, s70, 0xc000
	s_addc_u32 s5, s71, 0
	global_store_short v145, v48, s[4:5]
	s_add_u32 s4, s4, 0x300
	s_addc_u32 s5, s5, 0
	global_store_short_d16_hi v145, v48, s[4:5]
	s_add_u32 s4, s70, 0xc600
	s_addc_u32 s5, s71, 0
	global_store_short v145, v50, s[4:5]
	s_add_u32 s4, s4, 0x300
	s_addc_u32 s5, s5, 0
	global_store_short_d16_hi v145, v50, s[4:5]
	s_add_u32 s4, s70, 0xd800
	s_addc_u32 s5, s71, 0
	global_store_short v145, v52, s[4:5]
	s_add_u32 s4, s4, 0x300
	s_addc_u32 s5, s5, 0
	global_store_short_d16_hi v145, v52, s[4:5]
	s_add_u32 s4, s70, 0xde00
	s_addc_u32 s5, s71, 0
	global_store_short v145, v54, s[4:5]
	s_add_u32 s4, s4, 0x300
	s_addc_u32 s5, s5, 0
	global_store_short_d16_hi v145, v54, s[4:5]
	s_add_u32 s4, s70, 0xf000
	s_addc_u32 s5, s71, 0
	global_store_short v145, v56, s[4:5]
	s_add_u32 s4, s4, 0x300
	s_addc_u32 s5, s5, 0
	global_store_short_d16_hi v145, v56, s[4:5]
	s_add_u32 s4, s70, 0xf600
	s_addc_u32 s5, s71, 0
	global_store_short v145, v58, s[4:5]
	s_add_u32 s4, s4, 0x300
	s_addc_u32 s5, s5, 0
	global_store_short_d16_hi v145, v58, s[4:5]
	s_add_u32 s4, s70, 0x10800
	s_addc_u32 s5, s71, 0
	global_store_short v145, v60, s[4:5]
	s_add_u32 s4, s4, 0x300
	s_addc_u32 s5, s5, 0
	global_store_short_d16_hi v145, v60, s[4:5]
	s_add_u32 s4, s70, 0x10e00
	s_addc_u32 s5, s71, 0
	global_store_short v145, v62, s[4:5]
	s_add_u32 s4, s4, 0x300
	s_addc_u32 s5, s5, 0
	global_store_short_d16_hi v145, v62, s[4:5]
	v_mad_u32_u24 v128, v132, 32, v131
	ds_read_b64 v[96:97], v128
	v_mad_u32_u24 v128, v132, 33, v131
	ds_read_b64 v[98:99], v128
	v_mad_u32_u24 v128, v132, 34, v131
	ds_read_b64 v[100:101], v128
	v_mad_u32_u24 v128, v132, 35, v131
	ds_read_b64 v[102:103], v128
	v_mad_u32_u24 v128, v132, 40, v131
	ds_read_b64 v[104:105], v128
	v_mad_u32_u24 v128, v132, 41, v131
	ds_read_b64 v[106:107], v128
	v_mad_u32_u24 v128, v132, 42, v131
	ds_read_b64 v[108:109], v128
	v_mad_u32_u24 v128, v132, 43, v131
	ds_read_b64 v[110:111], v128
	v_mad_u32_u24 v128, v132, 48, v131
	ds_read_b64 v[64:65], v128
	v_mad_u32_u24 v128, v132, 49, v131
	ds_read_b64 v[66:67], v128
	v_mad_u32_u24 v128, v132, 50, v131
	ds_read_b64 v[68:69], v128
	v_mad_u32_u24 v128, v132, 51, v131
	ds_read_b64 v[70:71], v128
	v_mad_u32_u24 v128, v132, 56, v131
	ds_read_b64 v[72:73], v128
	v_mad_u32_u24 v128, v132, 57, v131
	ds_read_b64 v[74:75], v128
	v_mad_u32_u24 v128, v132, 58, v131
	ds_read_b64 v[76:77], v128
	v_mad_u32_u24 v128, v132, 59, v131
	ds_read_b64 v[78:79], v128
	v_mov_b32_dpp v32, v16 row_ror:8 row_mask:0xf bank_mask:0xf
	v_mov_b32_dpp v33, v17 row_ror:8 row_mask:0xf bank_mask:0xf
	v_mov_b32_dpp v34, v18 row_ror:8 row_mask:0xf bank_mask:0xf
	v_mov_b32_dpp v35, v19 row_ror:8 row_mask:0xf bank_mask:0xf
	v_mov_b32_dpp v36, v20 row_ror:8 row_mask:0xf bank_mask:0xf
	v_mov_b32_dpp v37, v21 row_ror:8 row_mask:0xf bank_mask:0xf
	v_mov_b32_dpp v38, v22 row_ror:8 row_mask:0xf bank_mask:0xf
	v_mov_b32_dpp v39, v23 row_ror:8 row_mask:0xf bank_mask:0xf
	v_mov_b32_dpp v40, v24 row_ror:8 row_mask:0xf bank_mask:0xf
	v_mov_b32_dpp v41, v25 row_ror:8 row_mask:0xf bank_mask:0xf
	v_mov_b32_dpp v42, v26 row_ror:8 row_mask:0xf bank_mask:0xf
	v_mov_b32_dpp v43, v27 row_ror:8 row_mask:0xf bank_mask:0xf
	v_mov_b32_dpp v44, v28 row_ror:8 row_mask:0xf bank_mask:0xf
	v_mov_b32_dpp v45, v29 row_ror:8 row_mask:0xf bank_mask:0xf
	v_mov_b32_dpp v46, v30 row_ror:8 row_mask:0xf bank_mask:0xf
	v_mov_b32_dpp v47, v31 row_ror:8 row_mask:0xf bank_mask:0xf
	s_waitcnt lgkmcnt(0)
	v_cndmask_b32_e64 v32, v32, -v32, s[36:37]
	v_mul_f32_e32 v16, v16, v96
	v_mul_f32_e32 v32, v97, v32
	v_add_f32_e32 v16, v16, v32
	v_mul_f32_e32 v16, 0x3e16c740, v16
	v_cndmask_b32_e64 v33, v33, -v33, s[36:37]
	v_mul_f32_e32 v17, v17, v98
	v_mul_f32_e32 v33, v99, v33
	v_add_f32_e32 v17, v17, v33
	v_mul_f32_e32 v17, 0x3e16c740, v17
	v_cndmask_b32_e64 v34, v34, -v34, s[36:37]
	v_mul_f32_e32 v18, v18, v100
	v_mul_f32_e32 v34, v101, v34
	v_add_f32_e32 v18, v18, v34
	v_mul_f32_e32 v18, 0x3e16c740, v18
	v_cndmask_b32_e64 v35, v35, -v35, s[36:37]
	v_mul_f32_e32 v19, v19, v102
	v_mul_f32_e32 v35, v103, v35
	v_add_f32_e32 v19, v19, v35
	v_mul_f32_e32 v19, 0x3e16c740, v19
	v_cndmask_b32_e64 v36, v36, -v36, s[36:37]
	v_mul_f32_e32 v20, v20, v104
	v_mul_f32_e32 v36, v105, v36
	v_add_f32_e32 v20, v20, v36
	v_mul_f32_e32 v20, 0x3e16c740, v20
	v_cndmask_b32_e64 v37, v37, -v37, s[36:37]
	v_mul_f32_e32 v21, v21, v106
	v_mul_f32_e32 v37, v107, v37
	v_add_f32_e32 v21, v21, v37
	v_mul_f32_e32 v21, 0x3e16c740, v21
	v_cndmask_b32_e64 v38, v38, -v38, s[36:37]
	v_mul_f32_e32 v22, v22, v108
	v_mul_f32_e32 v38, v109, v38
	v_add_f32_e32 v22, v22, v38
	v_mul_f32_e32 v22, 0x3e16c740, v22
	v_cndmask_b32_e64 v39, v39, -v39, s[36:37]
	v_mul_f32_e32 v23, v23, v110
	v_mul_f32_e32 v39, v111, v39
	v_add_f32_e32 v23, v23, v39
	v_mul_f32_e32 v23, 0x3e16c740, v23
	v_cndmask_b32_e64 v40, v40, -v40, s[36:37]
	v_mul_f32_e32 v24, v24, v64
	v_mul_f32_e32 v40, v65, v40
	v_add_f32_e32 v24, v24, v40
	v_mul_f32_e32 v24, 0x3e16c740, v24
	v_cndmask_b32_e64 v41, v41, -v41, s[36:37]
	v_mul_f32_e32 v25, v25, v66
	v_mul_f32_e32 v41, v67, v41
	v_add_f32_e32 v25, v25, v41
	v_mul_f32_e32 v25, 0x3e16c740, v25
	v_cndmask_b32_e64 v42, v42, -v42, s[36:37]
	v_mul_f32_e32 v26, v26, v68
	v_mul_f32_e32 v42, v69, v42
	v_add_f32_e32 v26, v26, v42
	v_mul_f32_e32 v26, 0x3e16c740, v26
	v_cndmask_b32_e64 v43, v43, -v43, s[36:37]
	v_mul_f32_e32 v27, v27, v70
	v_mul_f32_e32 v43, v71, v43
	v_add_f32_e32 v27, v27, v43
	v_mul_f32_e32 v27, 0x3e16c740, v27
	v_cndmask_b32_e64 v44, v44, -v44, s[36:37]
	v_mul_f32_e32 v28, v28, v72
	v_mul_f32_e32 v44, v73, v44
	v_add_f32_e32 v28, v28, v44
	v_mul_f32_e32 v28, 0x3e16c740, v28
	v_cndmask_b32_e64 v45, v45, -v45, s[36:37]
	v_mul_f32_e32 v29, v29, v74
	v_mul_f32_e32 v45, v75, v45
	v_add_f32_e32 v29, v29, v45
	v_mul_f32_e32 v29, 0x3e16c740, v29
	v_cndmask_b32_e64 v46, v46, -v46, s[36:37]
	v_mul_f32_e32 v30, v30, v76
	v_mul_f32_e32 v46, v77, v46
	v_add_f32_e32 v30, v30, v46
	v_mul_f32_e32 v30, 0x3e16c740, v30
	v_cndmask_b32_e64 v47, v47, -v47, s[36:37]
	v_mul_f32_e32 v31, v31, v78
	v_mul_f32_e32 v47, v79, v47
	v_add_f32_e32 v31, v31, v47
	v_mul_f32_e32 v31, 0x3e16c740, v31
	v_cvt_pk_bf16_f32 v16, v16, v17
	v_cvt_pk_bf16_f32 v18, v18, v19
	v_cvt_pk_bf16_f32 v20, v20, v21
	v_cvt_pk_bf16_f32 v22, v22, v23
	v_cvt_pk_bf16_f32 v24, v24, v25
	v_cvt_pk_bf16_f32 v26, v26, v27
	v_cvt_pk_bf16_f32 v28, v28, v29
	v_cvt_pk_bf16_f32 v30, v30, v31
	s_add_u32 s4, s70, 0x12000
	s_addc_u32 s5, s71, 0
	global_store_short v145, v16, s[4:5]
	s_add_u32 s4, s4, 0x300
	s_addc_u32 s5, s5, 0
	global_store_short_d16_hi v145, v16, s[4:5]
	s_add_u32 s4, s70, 0x12600
	s_addc_u32 s5, s71, 0
	global_store_short v145, v18, s[4:5]
	s_add_u32 s4, s4, 0x300
	s_addc_u32 s5, s5, 0
	global_store_short_d16_hi v145, v18, s[4:5]
	s_add_u32 s4, s70, 0x13800
	s_addc_u32 s5, s71, 0
	global_store_short v145, v20, s[4:5]
	s_add_u32 s4, s4, 0x300
	s_addc_u32 s5, s5, 0
	global_store_short_d16_hi v145, v20, s[4:5]
	s_add_u32 s4, s70, 0x13e00
	s_addc_u32 s5, s71, 0
	global_store_short v145, v22, s[4:5]
	s_add_u32 s4, s4, 0x300
	s_addc_u32 s5, s5, 0
	global_store_short_d16_hi v145, v22, s[4:5]
	s_add_u32 s4, s70, 0x15000
	s_addc_u32 s5, s71, 0
	global_store_short v145, v24, s[4:5]
	s_add_u32 s4, s4, 0x300
	s_addc_u32 s5, s5, 0
	global_store_short_d16_hi v145, v24, s[4:5]
	s_add_u32 s4, s70, 0x15600
	s_addc_u32 s5, s71, 0
	global_store_short v145, v26, s[4:5]
	s_add_u32 s4, s4, 0x300
	s_addc_u32 s5, s5, 0
	global_store_short_d16_hi v145, v26, s[4:5]
	s_add_u32 s4, s70, 0x16800
	s_addc_u32 s5, s71, 0
	global_store_short v145, v28, s[4:5]
	s_add_u32 s4, s4, 0x300
	s_addc_u32 s5, s5, 0
	global_store_short_d16_hi v145, v28, s[4:5]
	s_add_u32 s4, s70, 0x16e00
	s_addc_u32 s5, s71, 0
	global_store_short v145, v30, s[4:5]
	s_add_u32 s4, s4, 0x300
	s_addc_u32 s5, s5, 0
	global_store_short_d16_hi v145, v30, s[4:5]
	s_branch .LBB0_1223
.Lmq_rope1:
	v_mul_f32_e32 v112, 0x3e16c740, v112
	v_mul_f32_e32 v113, 0x3e16c740, v113
	v_cvt_pk_bf16_f32 v112, v112, v113
	v_mul_f32_e32 v114, 0x3e16c740, v114
	v_mul_f32_e32 v115, 0x3e16c740, v115
	v_cvt_pk_bf16_f32 v114, v114, v115
	v_mul_f32_e32 v116, 0x3e16c740, v116
	v_mul_f32_e32 v117, 0x3e16c740, v117
	v_cvt_pk_bf16_f32 v116, v116, v117
	v_mul_f32_e32 v118, 0x3e16c740, v118
	v_mul_f32_e32 v119, 0x3e16c740, v119
	v_cvt_pk_bf16_f32 v118, v118, v119
	v_mul_f32_e32 v120, 0x3e16c740, v120
	v_mul_f32_e32 v121, 0x3e16c740, v121
	v_cvt_pk_bf16_f32 v120, v120, v121
	v_mul_f32_e32 v122, 0x3e16c740, v122
	v_mul_f32_e32 v123, 0x3e16c740, v123
	v_cvt_pk_bf16_f32 v122, v122, v123
	v_mul_f32_e32 v124, 0x3e16c740, v124
	v_mul_f32_e32 v125, 0x3e16c740, v125
	v_cvt_pk_bf16_f32 v124, v124, v125
	v_mul_f32_e32 v126, 0x3e16c740, v126
	v_mul_f32_e32 v127, 0x3e16c740, v127
	v_cvt_pk_bf16_f32 v126, v126, v127
	s_mov_b32 s4, s70
	s_mov_b32 s5, s71
	global_store_short v145, v112, s[4:5]
	s_add_u32 s4, s4, 0x300
	s_addc_u32 s5, s5, 0
	global_store_short_d16_hi v145, v112, s[4:5]
	s_add_u32 s4, s70, 0x600
	s_addc_u32 s5, s71, 0
	global_store_short v145, v114, s[4:5]
	s_add_u32 s4, s4, 0x300
	s_addc_u32 s5, s5, 0
	global_store_short_d16_hi v145, v114, s[4:5]
	s_add_u32 s4, s70, 0x1800
	s_addc_u32 s5, s71, 0
	global_store_short v145, v116, s[4:5]
	s_add_u32 s4, s4, 0x300
	s_addc_u32 s5, s5, 0
	global_store_short_d16_hi v145, v116, s[4:5]
	s_add_u32 s4, s70, 0x1e00
	s_addc_u32 s5, s71, 0
	global_store_short v145, v118, s[4:5]
	s_add_u32 s4, s4, 0x300
	s_addc_u32 s5, s5, 0
	global_store_short_d16_hi v145, v118, s[4:5]
	s_add_u32 s4, s70, 0x3000
	s_addc_u32 s5, s71, 0
	global_store_short v145, v120, s[4:5]
	s_add_u32 s4, s4, 0x300
	s_addc_u32 s5, s5, 0
	global_store_short_d16_hi v145, v120, s[4:5]
	s_add_u32 s4, s70, 0x3600
	s_addc_u32 s5, s71, 0
	global_store_short v145, v122, s[4:5]
	s_add_u32 s4, s4, 0x300
	s_addc_u32 s5, s5, 0
	global_store_short_d16_hi v145, v122, s[4:5]
	s_add_u32 s4, s70, 0x4800
	s_addc_u32 s5, s71, 0
	global_store_short v145, v124, s[4:5]
	s_add_u32 s4, s4, 0x300
	s_addc_u32 s5, s5, 0
	global_store_short_d16_hi v145, v124, s[4:5]
	s_add_u32 s4, s70, 0x4e00
	s_addc_u32 s5, s71, 0
	global_store_short v145, v126, s[4:5]
	s_add_u32 s4, s4, 0x300
	s_addc_u32 s5, s5, 0
	global_store_short_d16_hi v145, v126, s[4:5]
	v_mul_f32_e32 v80, 0x3e16c740, v80
	v_mul_f32_e32 v81, 0x3e16c740, v81
	v_cvt_pk_bf16_f32 v80, v80, v81
	v_mul_f32_e32 v82, 0x3e16c740, v82
	v_mul_f32_e32 v83, 0x3e16c740, v83
	v_cvt_pk_bf16_f32 v82, v82, v83
	v_mul_f32_e32 v84, 0x3e16c740, v84
	v_mul_f32_e32 v85, 0x3e16c740, v85
	v_cvt_pk_bf16_f32 v84, v84, v85
	v_mul_f32_e32 v86, 0x3e16c740, v86
	v_mul_f32_e32 v87, 0x3e16c740, v87
	v_cvt_pk_bf16_f32 v86, v86, v87
	v_mul_f32_e32 v88, 0x3e16c740, v88
	v_mul_f32_e32 v89, 0x3e16c740, v89
	v_cvt_pk_bf16_f32 v88, v88, v89
	v_mul_f32_e32 v90, 0x3e16c740, v90
	v_mul_f32_e32 v91, 0x3e16c740, v91
	v_cvt_pk_bf16_f32 v90, v90, v91
	v_mul_f32_e32 v92, 0x3e16c740, v92
	v_mul_f32_e32 v93, 0x3e16c740, v93
	v_cvt_pk_bf16_f32 v92, v92, v93
	v_mul_f32_e32 v94, 0x3e16c740, v94
	v_mul_f32_e32 v95, 0x3e16c740, v95
	v_cvt_pk_bf16_f32 v94, v94, v95
	s_add_u32 s4, s70, 0x6000
	s_addc_u32 s5, s71, 0
	global_store_short v145, v80, s[4:5]
	s_add_u32 s4, s4, 0x300
	s_addc_u32 s5, s5, 0
	global_store_short_d16_hi v145, v80, s[4:5]
	s_add_u32 s4, s70, 0x6600
	s_addc_u32 s5, s71, 0
	global_store_short v145, v82, s[4:5]
	s_add_u32 s4, s4, 0x300
	s_addc_u32 s5, s5, 0
	global_store_short_d16_hi v145, v82, s[4:5]
	s_add_u32 s4, s70, 0x7800
	s_addc_u32 s5, s71, 0
	global_store_short v145, v84, s[4:5]
	s_add_u32 s4, s4, 0x300
	s_addc_u32 s5, s5, 0
	global_store_short_d16_hi v145, v84, s[4:5]
	s_add_u32 s4, s70, 0x7e00
	s_addc_u32 s5, s71, 0
	global_store_short v145, v86, s[4:5]
	s_add_u32 s4, s4, 0x300
	s_addc_u32 s5, s5, 0
	global_store_short_d16_hi v145, v86, s[4:5]
	s_add_u32 s4, s70, 0x9000
	s_addc_u32 s5, s71, 0
	global_store_short v145, v88, s[4:5]
	s_add_u32 s4, s4, 0x300
	s_addc_u32 s5, s5, 0
	global_store_short_d16_hi v145, v88, s[4:5]
	s_add_u32 s4, s70, 0x9600
	s_addc_u32 s5, s71, 0
	global_store_short v145, v90, s[4:5]
	s_add_u32 s4, s4, 0x300
	s_addc_u32 s5, s5, 0
	global_store_short_d16_hi v145, v90, s[4:5]
	s_add_u32 s4, s70, 0xa800
	s_addc_u32 s5, s71, 0
	global_store_short v145, v92, s[4:5]
	s_add_u32 s4, s4, 0x300
	s_addc_u32 s5, s5, 0
	global_store_short_d16_hi v145, v92, s[4:5]
	s_add_u32 s4, s70, 0xae00
	s_addc_u32 s5, s71, 0
	global_store_short v145, v94, s[4:5]
	s_add_u32 s4, s4, 0x300
	s_addc_u32 s5, s5, 0
	global_store_short_d16_hi v145, v94, s[4:5]
	v_mul_f32_e32 v48, 0x3e16c740, v48
	v_mul_f32_e32 v49, 0x3e16c740, v49
	v_cvt_pk_bf16_f32 v48, v48, v49
	v_mul_f32_e32 v50, 0x3e16c740, v50
	v_mul_f32_e32 v51, 0x3e16c740, v51
	v_cvt_pk_bf16_f32 v50, v50, v51
	v_mul_f32_e32 v52, 0x3e16c740, v52
	v_mul_f32_e32 v53, 0x3e16c740, v53
	v_cvt_pk_bf16_f32 v52, v52, v53
	v_mul_f32_e32 v54, 0x3e16c740, v54
	v_mul_f32_e32 v55, 0x3e16c740, v55
	v_cvt_pk_bf16_f32 v54, v54, v55
	v_mul_f32_e32 v56, 0x3e16c740, v56
	v_mul_f32_e32 v57, 0x3e16c740, v57
	v_cvt_pk_bf16_f32 v56, v56, v57
	v_mul_f32_e32 v58, 0x3e16c740, v58
	v_mul_f32_e32 v59, 0x3e16c740, v59
	v_cvt_pk_bf16_f32 v58, v58, v59
	v_mul_f32_e32 v60, 0x3e16c740, v60
	v_mul_f32_e32 v61, 0x3e16c740, v61
	v_cvt_pk_bf16_f32 v60, v60, v61
	v_mul_f32_e32 v62, 0x3e16c740, v62
	v_mul_f32_e32 v63, 0x3e16c740, v63
	v_cvt_pk_bf16_f32 v62, v62, v63
	s_add_u32 s4, s70, 0xc000
	s_addc_u32 s5, s71, 0
	global_store_short v145, v48, s[4:5]
	s_add_u32 s4, s4, 0x300
	s_addc_u32 s5, s5, 0
	global_store_short_d16_hi v145, v48, s[4:5]
	s_add_u32 s4, s70, 0xc600
	s_addc_u32 s5, s71, 0
	global_store_short v145, v50, s[4:5]
	s_add_u32 s4, s4, 0x300
	s_addc_u32 s5, s5, 0
	global_store_short_d16_hi v145, v50, s[4:5]
	s_add_u32 s4, s70, 0xd800
	s_addc_u32 s5, s71, 0
	global_store_short v145, v52, s[4:5]
	s_add_u32 s4, s4, 0x300
	s_addc_u32 s5, s5, 0
	global_store_short_d16_hi v145, v52, s[4:5]
	s_add_u32 s4, s70, 0xde00
	s_addc_u32 s5, s71, 0
	global_store_short v145, v54, s[4:5]
	s_add_u32 s4, s4, 0x300
	s_addc_u32 s5, s5, 0
	global_store_short_d16_hi v145, v54, s[4:5]
	s_add_u32 s4, s70, 0xf000
	s_addc_u32 s5, s71, 0
	global_store_short v145, v56, s[4:5]
	s_add_u32 s4, s4, 0x300
	s_addc_u32 s5, s5, 0
	global_store_short_d16_hi v145, v56, s[4:5]
	s_add_u32 s4, s70, 0xf600
	s_addc_u32 s5, s71, 0
	global_store_short v145, v58, s[4:5]
	s_add_u32 s4, s4, 0x300
	s_addc_u32 s5, s5, 0
	global_store_short_d16_hi v145, v58, s[4:5]
	s_add_u32 s4, s70, 0x10800
	s_addc_u32 s5, s71, 0
	global_store_short v145, v60, s[4:5]
	s_add_u32 s4, s4, 0x300
	s_addc_u32 s5, s5, 0
	global_store_short_d16_hi v145, v60, s[4:5]
	s_add_u32 s4, s70, 0x10e00
	s_addc_u32 s5, s71, 0
	global_store_short v145, v62, s[4:5]
	s_add_u32 s4, s4, 0x300
	s_addc_u32 s5, s5, 0
	global_store_short_d16_hi v145, v62, s[4:5]
	v_mul_f32_e32 v16, 0x3e16c740, v16
	v_mul_f32_e32 v17, 0x3e16c740, v17
	v_cvt_pk_bf16_f32 v16, v16, v17
	v_mul_f32_e32 v18, 0x3e16c740, v18
	v_mul_f32_e32 v19, 0x3e16c740, v19
	v_cvt_pk_bf16_f32 v18, v18, v19
	v_mul_f32_e32 v20, 0x3e16c740, v20
	v_mul_f32_e32 v21, 0x3e16c740, v21
	v_cvt_pk_bf16_f32 v20, v20, v21
	v_mul_f32_e32 v22, 0x3e16c740, v22
	v_mul_f32_e32 v23, 0x3e16c740, v23
	v_cvt_pk_bf16_f32 v22, v22, v23
	v_mul_f32_e32 v24, 0x3e16c740, v24
	v_mul_f32_e32 v25, 0x3e16c740, v25
	v_cvt_pk_bf16_f32 v24, v24, v25
	v_mul_f32_e32 v26, 0x3e16c740, v26
	v_mul_f32_e32 v27, 0x3e16c740, v27
	v_cvt_pk_bf16_f32 v26, v26, v27
	v_mul_f32_e32 v28, 0x3e16c740, v28
	v_mul_f32_e32 v29, 0x3e16c740, v29
	v_cvt_pk_bf16_f32 v28, v28, v29
	v_mul_f32_e32 v30, 0x3e16c740, v30
	v_mul_f32_e32 v31, 0x3e16c740, v31
	v_cvt_pk_bf16_f32 v30, v30, v31
	s_add_u32 s4, s70, 0x12000
	s_addc_u32 s5, s71, 0
	global_store_short v145, v16, s[4:5]
	s_add_u32 s4, s4, 0x300
	s_addc_u32 s5, s5, 0
	global_store_short_d16_hi v145, v16, s[4:5]
	s_add_u32 s4, s70, 0x12600
	s_addc_u32 s5, s71, 0
	global_store_short v145, v18, s[4:5]
	s_add_u32 s4, s4, 0x300
	s_addc_u32 s5, s5, 0
	global_store_short_d16_hi v145, v18, s[4:5]
	s_add_u32 s4, s70, 0x13800
	s_addc_u32 s5, s71, 0
	global_store_short v145, v20, s[4:5]
	s_add_u32 s4, s4, 0x300
	s_addc_u32 s5, s5, 0
	global_store_short_d16_hi v145, v20, s[4:5]
	s_add_u32 s4, s70, 0x13e00
	s_addc_u32 s5, s71, 0
	global_store_short v145, v22, s[4:5]
	s_add_u32 s4, s4, 0x300
	s_addc_u32 s5, s5, 0
	global_store_short_d16_hi v145, v22, s[4:5]
	s_add_u32 s4, s70, 0x15000
	s_addc_u32 s5, s71, 0
	global_store_short v145, v24, s[4:5]
	s_add_u32 s4, s4, 0x300
	s_addc_u32 s5, s5, 0
	global_store_short_d16_hi v145, v24, s[4:5]
	s_add_u32 s4, s70, 0x15600
	s_addc_u32 s5, s71, 0
	global_store_short v145, v26, s[4:5]
	s_add_u32 s4, s4, 0x300
	s_addc_u32 s5, s5, 0
	global_store_short_d16_hi v145, v26, s[4:5]
	s_add_u32 s4, s70, 0x16800
	s_addc_u32 s5, s71, 0
	global_store_short v145, v28, s[4:5]
	s_add_u32 s4, s4, 0x300
	s_addc_u32 s5, s5, 0
	global_store_short_d16_hi v145, v28, s[4:5]
	s_add_u32 s4, s70, 0x16e00
	s_addc_u32 s5, s71, 0
	global_store_short v145, v30, s[4:5]
	s_add_u32 s4, s4, 0x300
	s_addc_u32 s5, s5, 0
	global_store_short_d16_hi v145, v30, s[4:5]
	s_lshr_b32 s6, s55, 6
	v_lshrrev_b32_e32 v128, 6, v178
	v_add_u32_e32 v128, s6, v128
	v_lshlrev_b32_e32 v133, 3, v177
	v_and_b32_e32 v130, 15, v128
	v_lshl_or_b32 v130, v130, 6, v133
	v_add_u32_e32 v131, 1, v128
	v_and_b32_e32 v131, 15, v131
	v_lshl_or_b32 v131, v131, 6, v133
	v_and_b32_e32 v146, 4, v178
	v_lshl_or_b32 v146, v146, 6, v133
	v_cndmask_b32_e64 v130, v130, v146, s[38:39]
	v_cndmask_b32_e64 v131, v131, v146, s[38:39]
	v_add_u32_e32 v130, 0x20000, v130
	v_add_u32_e32 v131, 0x20000, v131
	v_cndmask_b32_e64 v132, 0, 64, s[38:39]
	v_mad_u32_u24 v128, v132, 0, v130
	ds_read_b64 v[112:113], v128
	v_mad_u32_u24 v128, v132, 1, v130
	ds_read_b64 v[114:115], v128
	v_mad_u32_u24 v128, v132, 2, v130
	ds_read_b64 v[116:117], v128
	v_mad_u32_u24 v128, v132, 3, v130
	ds_read_b64 v[118:119], v128
	v_mad_u32_u24 v128, v132, 8, v130
	ds_read_b64 v[120:121], v128
	v_mad_u32_u24 v128, v132, 9, v130
	ds_read_b64 v[122:123], v128
	v_mad_u32_u24 v128, v132, 10, v130
	ds_read_b64 v[124:125], v128
	v_mad_u32_u24 v128, v132, 11, v130
	ds_read_b64 v[126:127], v128
	v_mad_u32_u24 v128, v132, 16, v130
	ds_read_b64 v[80:81], v128
	v_mad_u32_u24 v128, v132, 17, v130
	ds_read_b64 v[82:83], v128
	v_mad_u32_u24 v128, v132, 18, v130
	ds_read_b64 v[84:85], v128
	v_mad_u32_u24 v128, v132, 19, v130
	ds_read_b64 v[86:87], v128
	v_mad_u32_u24 v128, v132, 24, v130
	ds_read_b64 v[88:89], v128
	v_mad_u32_u24 v128, v132, 25, v130
	ds_read_b64 v[90:91], v128
	v_mad_u32_u24 v128, v132, 26, v130
	ds_read_b64 v[92:93], v128
	v_mad_u32_u24 v128, v132, 27, v130
	ds_read_b64 v[94:95], v128
	v_mov_b32_dpp v48, v96 row_ror:8 row_mask:0xf bank_mask:0xf
	v_mov_b32_dpp v49, v97 row_ror:8 row_mask:0xf bank_mask:0xf
	v_mov_b32_dpp v50, v98 row_ror:8 row_mask:0xf bank_mask:0xf
	v_mov_b32_dpp v51, v99 row_ror:8 row_mask:0xf bank_mask:0xf
	v_mov_b32_dpp v52, v100 row_ror:8 row_mask:0xf bank_mask:0xf
	v_mov_b32_dpp v53, v101 row_ror:8 row_mask:0xf bank_mask:0xf
	v_mov_b32_dpp v54, v102 row_ror:8 row_mask:0xf bank_mask:0xf
	v_mov_b32_dpp v55, v103 row_ror:8 row_mask:0xf bank_mask:0xf
	v_mov_b32_dpp v56, v104 row_ror:8 row_mask:0xf bank_mask:0xf
	v_mov_b32_dpp v57, v105 row_ror:8 row_mask:0xf bank_mask:0xf
	v_mov_b32_dpp v58, v106 row_ror:8 row_mask:0xf bank_mask:0xf
	v_mov_b32_dpp v59, v107 row_ror:8 row_mask:0xf bank_mask:0xf
	v_mov_b32_dpp v60, v108 row_ror:8 row_mask:0xf bank_mask:0xf
	v_mov_b32_dpp v61, v109 row_ror:8 row_mask:0xf bank_mask:0xf
	v_mov_b32_dpp v62, v110 row_ror:8 row_mask:0xf bank_mask:0xf
	v_mov_b32_dpp v63, v111 row_ror:8 row_mask:0xf bank_mask:0xf
	s_waitcnt lgkmcnt(0)
	v_cndmask_b32_e64 v48, v48, -v48, s[36:37]
	v_mul_f32_e32 v96, v96, v112
	v_mul_f32_e32 v48, v113, v48
	v_add_f32_e32 v96, v96, v48
	v_mul_f32_e32 v96, 0x3e16c740, v96
	v_cndmask_b32_e64 v49, v49, -v49, s[36:37]
	v_mul_f32_e32 v97, v97, v114
	v_mul_f32_e32 v49, v115, v49
	v_add_f32_e32 v97, v97, v49
	v_mul_f32_e32 v97, 0x3e16c740, v97
	v_cndmask_b32_e64 v50, v50, -v50, s[36:37]
	v_mul_f32_e32 v98, v98, v116
	v_mul_f32_e32 v50, v117, v50
	v_add_f32_e32 v98, v98, v50
	v_mul_f32_e32 v98, 0x3e16c740, v98
	v_cndmask_b32_e64 v51, v51, -v51, s[36:37]
	v_mul_f32_e32 v99, v99, v118
	v_mul_f32_e32 v51, v119, v51
	v_add_f32_e32 v99, v99, v51
	v_mul_f32_e32 v99, 0x3e16c740, v99
	v_cndmask_b32_e64 v52, v52, -v52, s[36:37]
	v_mul_f32_e32 v100, v100, v120
	v_mul_f32_e32 v52, v121, v52
	v_add_f32_e32 v100, v100, v52
	v_mul_f32_e32 v100, 0x3e16c740, v100
	v_cndmask_b32_e64 v53, v53, -v53, s[36:37]
	v_mul_f32_e32 v101, v101, v122
	v_mul_f32_e32 v53, v123, v53
	v_add_f32_e32 v101, v101, v53
	v_mul_f32_e32 v101, 0x3e16c740, v101
	v_cndmask_b32_e64 v54, v54, -v54, s[36:37]
	v_mul_f32_e32 v102, v102, v124
	v_mul_f32_e32 v54, v125, v54
	v_add_f32_e32 v102, v102, v54
	v_mul_f32_e32 v102, 0x3e16c740, v102
	v_cndmask_b32_e64 v55, v55, -v55, s[36:37]
	v_mul_f32_e32 v103, v103, v126
	v_mul_f32_e32 v55, v127, v55
	v_add_f32_e32 v103, v103, v55
	v_mul_f32_e32 v103, 0x3e16c740, v103
	v_cndmask_b32_e64 v56, v56, -v56, s[36:37]
	v_mul_f32_e32 v104, v104, v80
	v_mul_f32_e32 v56, v81, v56
	v_add_f32_e32 v104, v104, v56
	v_mul_f32_e32 v104, 0x3e16c740, v104
	v_cndmask_b32_e64 v57, v57, -v57, s[36:37]
	v_mul_f32_e32 v105, v105, v82
	v_mul_f32_e32 v57, v83, v57
	v_add_f32_e32 v105, v105, v57
	v_mul_f32_e32 v105, 0x3e16c740, v105
	v_cndmask_b32_e64 v58, v58, -v58, s[36:37]
	v_mul_f32_e32 v106, v106, v84
	v_mul_f32_e32 v58, v85, v58
	v_add_f32_e32 v106, v106, v58
	v_mul_f32_e32 v106, 0x3e16c740, v106
	v_cndmask_b32_e64 v59, v59, -v59, s[36:37]
	v_mul_f32_e32 v107, v107, v86
	v_mul_f32_e32 v59, v87, v59
	v_add_f32_e32 v107, v107, v59
	v_mul_f32_e32 v107, 0x3e16c740, v107
	v_cndmask_b32_e64 v60, v60, -v60, s[36:37]
	v_mul_f32_e32 v108, v108, v88
	v_mul_f32_e32 v60, v89, v60
	v_add_f32_e32 v108, v108, v60
	v_mul_f32_e32 v108, 0x3e16c740, v108
	v_cndmask_b32_e64 v61, v61, -v61, s[36:37]
	v_mul_f32_e32 v109, v109, v90
	v_mul_f32_e32 v61, v91, v61
	v_add_f32_e32 v109, v109, v61
	v_mul_f32_e32 v109, 0x3e16c740, v109
	v_cndmask_b32_e64 v62, v62, -v62, s[36:37]
	v_mul_f32_e32 v110, v110, v92
	v_mul_f32_e32 v62, v93, v62
	v_add_f32_e32 v110, v110, v62
	v_mul_f32_e32 v110, 0x3e16c740, v110
	v_cndmask_b32_e64 v63, v63, -v63, s[36:37]
	v_mul_f32_e32 v111, v111, v94
	v_mul_f32_e32 v63, v95, v63
	v_add_f32_e32 v111, v111, v63
	v_mul_f32_e32 v111, 0x3e16c740, v111
	v_cvt_pk_bf16_f32 v96, v96, v97
	v_cvt_pk_bf16_f32 v98, v98, v99
	v_cvt_pk_bf16_f32 v100, v100, v101
	v_cvt_pk_bf16_f32 v102, v102, v103
	v_cvt_pk_bf16_f32 v104, v104, v105
	v_cvt_pk_bf16_f32 v106, v106, v107
	v_cvt_pk_bf16_f32 v108, v108, v109
	v_cvt_pk_bf16_f32 v110, v110, v111
	s_mov_b32 s4, s70
	s_mov_b32 s5, s71
	global_store_short v145, v96, s[4:5] offset:64
	s_add_u32 s4, s4, 0x300
	s_addc_u32 s5, s5, 0
	global_store_short_d16_hi v145, v96, s[4:5] offset:64
	s_add_u32 s4, s70, 0x600
	s_addc_u32 s5, s71, 0
	global_store_short v145, v98, s[4:5] offset:64
	s_add_u32 s4, s4, 0x300
	s_addc_u32 s5, s5, 0
	global_store_short_d16_hi v145, v98, s[4:5] offset:64
	s_add_u32 s4, s70, 0x1800
	s_addc_u32 s5, s71, 0
	global_store_short v145, v100, s[4:5] offset:64
	s_add_u32 s4, s4, 0x300
	s_addc_u32 s5, s5, 0
	global_store_short_d16_hi v145, v100, s[4:5] offset:64
	s_add_u32 s4, s70, 0x1e00
	s_addc_u32 s5, s71, 0
	global_store_short v145, v102, s[4:5] offset:64
	s_add_u32 s4, s4, 0x300
	s_addc_u32 s5, s5, 0
	global_store_short_d16_hi v145, v102, s[4:5] offset:64
	s_add_u32 s4, s70, 0x3000
	s_addc_u32 s5, s71, 0
	global_store_short v145, v104, s[4:5] offset:64
	s_add_u32 s4, s4, 0x300
	s_addc_u32 s5, s5, 0
	global_store_short_d16_hi v145, v104, s[4:5] offset:64
	s_add_u32 s4, s70, 0x3600
	s_addc_u32 s5, s71, 0
	global_store_short v145, v106, s[4:5] offset:64
	s_add_u32 s4, s4, 0x300
	s_addc_u32 s5, s5, 0
	global_store_short_d16_hi v145, v106, s[4:5] offset:64
	s_add_u32 s4, s70, 0x4800
	s_addc_u32 s5, s71, 0
	global_store_short v145, v108, s[4:5] offset:64
	s_add_u32 s4, s4, 0x300
	s_addc_u32 s5, s5, 0
	global_store_short_d16_hi v145, v108, s[4:5] offset:64
	s_add_u32 s4, s70, 0x4e00
	s_addc_u32 s5, s71, 0
	global_store_short v145, v110, s[4:5] offset:64
	s_add_u32 s4, s4, 0x300
	s_addc_u32 s5, s5, 0
	global_store_short_d16_hi v145, v110, s[4:5] offset:64
	v_mad_u32_u24 v128, v132, 32, v130
	ds_read_b64 v[112:113], v128
	v_mad_u32_u24 v128, v132, 33, v130
	ds_read_b64 v[114:115], v128
	v_mad_u32_u24 v128, v132, 34, v130
	ds_read_b64 v[116:117], v128
	v_mad_u32_u24 v128, v132, 35, v130
	ds_read_b64 v[118:119], v128
	v_mad_u32_u24 v128, v132, 40, v130
	ds_read_b64 v[120:121], v128
	v_mad_u32_u24 v128, v132, 41, v130
	ds_read_b64 v[122:123], v128
	v_mad_u32_u24 v128, v132, 42, v130
	ds_read_b64 v[124:125], v128
	v_mad_u32_u24 v128, v132, 43, v130
	ds_read_b64 v[126:127], v128
	v_mad_u32_u24 v128, v132, 48, v130
	ds_read_b64 v[80:81], v128
	v_mad_u32_u24 v128, v132, 49, v130
	ds_read_b64 v[82:83], v128
	v_mad_u32_u24 v128, v132, 50, v130
	ds_read_b64 v[84:85], v128
	v_mad_u32_u24 v128, v132, 51, v130
	ds_read_b64 v[86:87], v128
	v_mad_u32_u24 v128, v132, 56, v130
	ds_read_b64 v[88:89], v128
	v_mad_u32_u24 v128, v132, 57, v130
	ds_read_b64 v[90:91], v128
	v_mad_u32_u24 v128, v132, 58, v130
	ds_read_b64 v[92:93], v128
	v_mad_u32_u24 v128, v132, 59, v130
	ds_read_b64 v[94:95], v128
	v_mov_b32_dpp v48, v64 row_ror:8 row_mask:0xf bank_mask:0xf
	v_mov_b32_dpp v49, v65 row_ror:8 row_mask:0xf bank_mask:0xf
	v_mov_b32_dpp v50, v66 row_ror:8 row_mask:0xf bank_mask:0xf
	v_mov_b32_dpp v51, v67 row_ror:8 row_mask:0xf bank_mask:0xf
	v_mov_b32_dpp v52, v68 row_ror:8 row_mask:0xf bank_mask:0xf
	v_mov_b32_dpp v53, v69 row_ror:8 row_mask:0xf bank_mask:0xf
	v_mov_b32_dpp v54, v70 row_ror:8 row_mask:0xf bank_mask:0xf
	v_mov_b32_dpp v55, v71 row_ror:8 row_mask:0xf bank_mask:0xf
	v_mov_b32_dpp v56, v72 row_ror:8 row_mask:0xf bank_mask:0xf
	v_mov_b32_dpp v57, v73 row_ror:8 row_mask:0xf bank_mask:0xf
	v_mov_b32_dpp v58, v74 row_ror:8 row_mask:0xf bank_mask:0xf
	v_mov_b32_dpp v59, v75 row_ror:8 row_mask:0xf bank_mask:0xf
	v_mov_b32_dpp v60, v76 row_ror:8 row_mask:0xf bank_mask:0xf
	v_mov_b32_dpp v61, v77 row_ror:8 row_mask:0xf bank_mask:0xf
	v_mov_b32_dpp v62, v78 row_ror:8 row_mask:0xf bank_mask:0xf
	v_mov_b32_dpp v63, v79 row_ror:8 row_mask:0xf bank_mask:0xf
	s_waitcnt lgkmcnt(0)
	v_cndmask_b32_e64 v48, v48, -v48, s[36:37]
	v_mul_f32_e32 v64, v64, v112
	v_mul_f32_e32 v48, v113, v48
	v_add_f32_e32 v64, v64, v48
	v_mul_f32_e32 v64, 0x3e16c740, v64
	v_cndmask_b32_e64 v49, v49, -v49, s[36:37]
	v_mul_f32_e32 v65, v65, v114
	v_mul_f32_e32 v49, v115, v49
	v_add_f32_e32 v65, v65, v49
	v_mul_f32_e32 v65, 0x3e16c740, v65
	v_cndmask_b32_e64 v50, v50, -v50, s[36:37]
	v_mul_f32_e32 v66, v66, v116
	v_mul_f32_e32 v50, v117, v50
	v_add_f32_e32 v66, v66, v50
	v_mul_f32_e32 v66, 0x3e16c740, v66
	v_cndmask_b32_e64 v51, v51, -v51, s[36:37]
	v_mul_f32_e32 v67, v67, v118
	v_mul_f32_e32 v51, v119, v51
	v_add_f32_e32 v67, v67, v51
	v_mul_f32_e32 v67, 0x3e16c740, v67
	v_cndmask_b32_e64 v52, v52, -v52, s[36:37]
	v_mul_f32_e32 v68, v68, v120
	v_mul_f32_e32 v52, v121, v52
	v_add_f32_e32 v68, v68, v52
	v_mul_f32_e32 v68, 0x3e16c740, v68
	v_cndmask_b32_e64 v53, v53, -v53, s[36:37]
	v_mul_f32_e32 v69, v69, v122
	v_mul_f32_e32 v53, v123, v53
	v_add_f32_e32 v69, v69, v53
	v_mul_f32_e32 v69, 0x3e16c740, v69
	v_cndmask_b32_e64 v54, v54, -v54, s[36:37]
	v_mul_f32_e32 v70, v70, v124
	v_mul_f32_e32 v54, v125, v54
	v_add_f32_e32 v70, v70, v54
	v_mul_f32_e32 v70, 0x3e16c740, v70
	v_cndmask_b32_e64 v55, v55, -v55, s[36:37]
	v_mul_f32_e32 v71, v71, v126
	v_mul_f32_e32 v55, v127, v55
	v_add_f32_e32 v71, v71, v55
	v_mul_f32_e32 v71, 0x3e16c740, v71
	v_cndmask_b32_e64 v56, v56, -v56, s[36:37]
	v_mul_f32_e32 v72, v72, v80
	v_mul_f32_e32 v56, v81, v56
	v_add_f32_e32 v72, v72, v56
	v_mul_f32_e32 v72, 0x3e16c740, v72
	v_cndmask_b32_e64 v57, v57, -v57, s[36:37]
	v_mul_f32_e32 v73, v73, v82
	v_mul_f32_e32 v57, v83, v57
	v_add_f32_e32 v73, v73, v57
	v_mul_f32_e32 v73, 0x3e16c740, v73
	v_cndmask_b32_e64 v58, v58, -v58, s[36:37]
	v_mul_f32_e32 v74, v74, v84
	v_mul_f32_e32 v58, v85, v58
	v_add_f32_e32 v74, v74, v58
	v_mul_f32_e32 v74, 0x3e16c740, v74
	v_cndmask_b32_e64 v59, v59, -v59, s[36:37]
	v_mul_f32_e32 v75, v75, v86
	v_mul_f32_e32 v59, v87, v59
	v_add_f32_e32 v75, v75, v59
	v_mul_f32_e32 v75, 0x3e16c740, v75
	v_cndmask_b32_e64 v60, v60, -v60, s[36:37]
	v_mul_f32_e32 v76, v76, v88
	v_mul_f32_e32 v60, v89, v60
	v_add_f32_e32 v76, v76, v60
	v_mul_f32_e32 v76, 0x3e16c740, v76
	v_cndmask_b32_e64 v61, v61, -v61, s[36:37]
	v_mul_f32_e32 v77, v77, v90
	v_mul_f32_e32 v61, v91, v61
	v_add_f32_e32 v77, v77, v61
	v_mul_f32_e32 v77, 0x3e16c740, v77
	v_cndmask_b32_e64 v62, v62, -v62, s[36:37]
	v_mul_f32_e32 v78, v78, v92
	v_mul_f32_e32 v62, v93, v62
	v_add_f32_e32 v78, v78, v62
	v_mul_f32_e32 v78, 0x3e16c740, v78
	v_cndmask_b32_e64 v63, v63, -v63, s[36:37]
	v_mul_f32_e32 v79, v79, v94
	v_mul_f32_e32 v63, v95, v63
	v_add_f32_e32 v79, v79, v63
	v_mul_f32_e32 v79, 0x3e16c740, v79
	v_cvt_pk_bf16_f32 v64, v64, v65
	v_cvt_pk_bf16_f32 v66, v66, v67
	v_cvt_pk_bf16_f32 v68, v68, v69
	v_cvt_pk_bf16_f32 v70, v70, v71
	v_cvt_pk_bf16_f32 v72, v72, v73
	v_cvt_pk_bf16_f32 v74, v74, v75
	v_cvt_pk_bf16_f32 v76, v76, v77
	v_cvt_pk_bf16_f32 v78, v78, v79
	s_add_u32 s4, s70, 0x6000
	s_addc_u32 s5, s71, 0
	global_store_short v145, v64, s[4:5] offset:64
	s_add_u32 s4, s4, 0x300
	s_addc_u32 s5, s5, 0
	global_store_short_d16_hi v145, v64, s[4:5] offset:64
	s_add_u32 s4, s70, 0x6600
	s_addc_u32 s5, s71, 0
	global_store_short v145, v66, s[4:5] offset:64
	s_add_u32 s4, s4, 0x300
	s_addc_u32 s5, s5, 0
	global_store_short_d16_hi v145, v66, s[4:5] offset:64
	s_add_u32 s4, s70, 0x7800
	s_addc_u32 s5, s71, 0
	global_store_short v145, v68, s[4:5] offset:64
	s_add_u32 s4, s4, 0x300
	s_addc_u32 s5, s5, 0
	global_store_short_d16_hi v145, v68, s[4:5] offset:64
	s_add_u32 s4, s70, 0x7e00
	s_addc_u32 s5, s71, 0
	global_store_short v145, v70, s[4:5] offset:64
	s_add_u32 s4, s4, 0x300
	s_addc_u32 s5, s5, 0
	global_store_short_d16_hi v145, v70, s[4:5] offset:64
	s_add_u32 s4, s70, 0x9000
	s_addc_u32 s5, s71, 0
	global_store_short v145, v72, s[4:5] offset:64
	s_add_u32 s4, s4, 0x300
	s_addc_u32 s5, s5, 0
	global_store_short_d16_hi v145, v72, s[4:5] offset:64
	s_add_u32 s4, s70, 0x9600
	s_addc_u32 s5, s71, 0
	global_store_short v145, v74, s[4:5] offset:64
	s_add_u32 s4, s4, 0x300
	s_addc_u32 s5, s5, 0
	global_store_short_d16_hi v145, v74, s[4:5] offset:64
	s_add_u32 s4, s70, 0xa800
	s_addc_u32 s5, s71, 0
	global_store_short v145, v76, s[4:5] offset:64
	s_add_u32 s4, s4, 0x300
	s_addc_u32 s5, s5, 0
	global_store_short_d16_hi v145, v76, s[4:5] offset:64
	s_add_u32 s4, s70, 0xae00
	s_addc_u32 s5, s71, 0
	global_store_short v145, v78, s[4:5] offset:64
	s_add_u32 s4, s4, 0x300
	s_addc_u32 s5, s5, 0
	global_store_short_d16_hi v145, v78, s[4:5] offset:64
	v_mad_u32_u24 v128, v132, 0, v131
	ds_read_b64 v[112:113], v128
	v_mad_u32_u24 v128, v132, 1, v131
	ds_read_b64 v[114:115], v128
	v_mad_u32_u24 v128, v132, 2, v131
	ds_read_b64 v[116:117], v128
	v_mad_u32_u24 v128, v132, 3, v131
	ds_read_b64 v[118:119], v128
	v_mad_u32_u24 v128, v132, 8, v131
	ds_read_b64 v[120:121], v128
	v_mad_u32_u24 v128, v132, 9, v131
	ds_read_b64 v[122:123], v128
	v_mad_u32_u24 v128, v132, 10, v131
	ds_read_b64 v[124:125], v128
	v_mad_u32_u24 v128, v132, 11, v131
	ds_read_b64 v[126:127], v128
	v_mad_u32_u24 v128, v132, 16, v131
	ds_read_b64 v[80:81], v128
	v_mad_u32_u24 v128, v132, 17, v131
	ds_read_b64 v[82:83], v128
	v_mad_u32_u24 v128, v132, 18, v131
	ds_read_b64 v[84:85], v128
	v_mad_u32_u24 v128, v132, 19, v131
	ds_read_b64 v[86:87], v128
	v_mad_u32_u24 v128, v132, 24, v131
	ds_read_b64 v[88:89], v128
	v_mad_u32_u24 v128, v132, 25, v131
	ds_read_b64 v[90:91], v128
	v_mad_u32_u24 v128, v132, 26, v131
	ds_read_b64 v[92:93], v128
	v_mad_u32_u24 v128, v132, 27, v131
	ds_read_b64 v[94:95], v128
	v_mov_b32_dpp v48, v32 row_ror:8 row_mask:0xf bank_mask:0xf
	v_mov_b32_dpp v49, v33 row_ror:8 row_mask:0xf bank_mask:0xf
	v_mov_b32_dpp v50, v34 row_ror:8 row_mask:0xf bank_mask:0xf
	v_mov_b32_dpp v51, v35 row_ror:8 row_mask:0xf bank_mask:0xf
	v_mov_b32_dpp v52, v36 row_ror:8 row_mask:0xf bank_mask:0xf
	v_mov_b32_dpp v53, v37 row_ror:8 row_mask:0xf bank_mask:0xf
	v_mov_b32_dpp v54, v38 row_ror:8 row_mask:0xf bank_mask:0xf
	v_mov_b32_dpp v55, v39 row_ror:8 row_mask:0xf bank_mask:0xf
	v_mov_b32_dpp v56, v40 row_ror:8 row_mask:0xf bank_mask:0xf
	v_mov_b32_dpp v57, v41 row_ror:8 row_mask:0xf bank_mask:0xf
	v_mov_b32_dpp v58, v42 row_ror:8 row_mask:0xf bank_mask:0xf
	v_mov_b32_dpp v59, v43 row_ror:8 row_mask:0xf bank_mask:0xf
	v_mov_b32_dpp v60, v44 row_ror:8 row_mask:0xf bank_mask:0xf
	v_mov_b32_dpp v61, v45 row_ror:8 row_mask:0xf bank_mask:0xf
	v_mov_b32_dpp v62, v46 row_ror:8 row_mask:0xf bank_mask:0xf
	v_mov_b32_dpp v63, v47 row_ror:8 row_mask:0xf bank_mask:0xf
	s_waitcnt lgkmcnt(0)
	v_cndmask_b32_e64 v48, v48, -v48, s[36:37]
	v_mul_f32_e32 v32, v32, v112
	v_mul_f32_e32 v48, v113, v48
	v_add_f32_e32 v32, v32, v48
	v_mul_f32_e32 v32, 0x3e16c740, v32
	v_cndmask_b32_e64 v49, v49, -v49, s[36:37]
	v_mul_f32_e32 v33, v33, v114
	v_mul_f32_e32 v49, v115, v49
	v_add_f32_e32 v33, v33, v49
	v_mul_f32_e32 v33, 0x3e16c740, v33
	v_cndmask_b32_e64 v50, v50, -v50, s[36:37]
	v_mul_f32_e32 v34, v34, v116
	v_mul_f32_e32 v50, v117, v50
	v_add_f32_e32 v34, v34, v50
	v_mul_f32_e32 v34, 0x3e16c740, v34
	v_cndmask_b32_e64 v51, v51, -v51, s[36:37]
	v_mul_f32_e32 v35, v35, v118
	v_mul_f32_e32 v51, v119, v51
	v_add_f32_e32 v35, v35, v51
	v_mul_f32_e32 v35, 0x3e16c740, v35
	v_cndmask_b32_e64 v52, v52, -v52, s[36:37]
	v_mul_f32_e32 v36, v36, v120
	v_mul_f32_e32 v52, v121, v52
	v_add_f32_e32 v36, v36, v52
	v_mul_f32_e32 v36, 0x3e16c740, v36
	v_cndmask_b32_e64 v53, v53, -v53, s[36:37]
	v_mul_f32_e32 v37, v37, v122
	v_mul_f32_e32 v53, v123, v53
	v_add_f32_e32 v37, v37, v53
	v_mul_f32_e32 v37, 0x3e16c740, v37
	v_cndmask_b32_e64 v54, v54, -v54, s[36:37]
	v_mul_f32_e32 v38, v38, v124
	v_mul_f32_e32 v54, v125, v54
	v_add_f32_e32 v38, v38, v54
	v_mul_f32_e32 v38, 0x3e16c740, v38
	v_cndmask_b32_e64 v55, v55, -v55, s[36:37]
	v_mul_f32_e32 v39, v39, v126
	v_mul_f32_e32 v55, v127, v55
	v_add_f32_e32 v39, v39, v55
	v_mul_f32_e32 v39, 0x3e16c740, v39
	v_cndmask_b32_e64 v56, v56, -v56, s[36:37]
	v_mul_f32_e32 v40, v40, v80
	v_mul_f32_e32 v56, v81, v56
	v_add_f32_e32 v40, v40, v56
	v_mul_f32_e32 v40, 0x3e16c740, v40
	v_cndmask_b32_e64 v57, v57, -v57, s[36:37]
	v_mul_f32_e32 v41, v41, v82
	v_mul_f32_e32 v57, v83, v57
	v_add_f32_e32 v41, v41, v57
	v_mul_f32_e32 v41, 0x3e16c740, v41
	v_cndmask_b32_e64 v58, v58, -v58, s[36:37]
	v_mul_f32_e32 v42, v42, v84
	v_mul_f32_e32 v58, v85, v58
	v_add_f32_e32 v42, v42, v58
	v_mul_f32_e32 v42, 0x3e16c740, v42
	v_cndmask_b32_e64 v59, v59, -v59, s[36:37]
	v_mul_f32_e32 v43, v43, v86
	v_mul_f32_e32 v59, v87, v59
	v_add_f32_e32 v43, v43, v59
	v_mul_f32_e32 v43, 0x3e16c740, v43
	v_cndmask_b32_e64 v60, v60, -v60, s[36:37]
	v_mul_f32_e32 v44, v44, v88
	v_mul_f32_e32 v60, v89, v60
	v_add_f32_e32 v44, v44, v60
	v_mul_f32_e32 v44, 0x3e16c740, v44
	v_cndmask_b32_e64 v61, v61, -v61, s[36:37]
	v_mul_f32_e32 v45, v45, v90
	v_mul_f32_e32 v61, v91, v61
	v_add_f32_e32 v45, v45, v61
	v_mul_f32_e32 v45, 0x3e16c740, v45
	v_cndmask_b32_e64 v62, v62, -v62, s[36:37]
	v_mul_f32_e32 v46, v46, v92
	v_mul_f32_e32 v62, v93, v62
	v_add_f32_e32 v46, v46, v62
	v_mul_f32_e32 v46, 0x3e16c740, v46
	v_cndmask_b32_e64 v63, v63, -v63, s[36:37]
	v_mul_f32_e32 v47, v47, v94
	v_mul_f32_e32 v63, v95, v63
	v_add_f32_e32 v47, v47, v63
	v_mul_f32_e32 v47, 0x3e16c740, v47
	v_cvt_pk_bf16_f32 v32, v32, v33
	v_cvt_pk_bf16_f32 v34, v34, v35
	v_cvt_pk_bf16_f32 v36, v36, v37
	v_cvt_pk_bf16_f32 v38, v38, v39
	v_cvt_pk_bf16_f32 v40, v40, v41
	v_cvt_pk_bf16_f32 v42, v42, v43
	v_cvt_pk_bf16_f32 v44, v44, v45
	v_cvt_pk_bf16_f32 v46, v46, v47
	s_add_u32 s4, s70, 0xc000
	s_addc_u32 s5, s71, 0
	global_store_short v145, v32, s[4:5] offset:64
	s_add_u32 s4, s4, 0x300
	s_addc_u32 s5, s5, 0
	global_store_short_d16_hi v145, v32, s[4:5] offset:64
	s_add_u32 s4, s70, 0xc600
	s_addc_u32 s5, s71, 0
	global_store_short v145, v34, s[4:5] offset:64
	s_add_u32 s4, s4, 0x300
	s_addc_u32 s5, s5, 0
	global_store_short_d16_hi v145, v34, s[4:5] offset:64
	s_add_u32 s4, s70, 0xd800
	s_addc_u32 s5, s71, 0
	global_store_short v145, v36, s[4:5] offset:64
	s_add_u32 s4, s4, 0x300
	s_addc_u32 s5, s5, 0
	global_store_short_d16_hi v145, v36, s[4:5] offset:64
	s_add_u32 s4, s70, 0xde00
	s_addc_u32 s5, s71, 0
	global_store_short v145, v38, s[4:5] offset:64
	s_add_u32 s4, s4, 0x300
	s_addc_u32 s5, s5, 0
	global_store_short_d16_hi v145, v38, s[4:5] offset:64
	s_add_u32 s4, s70, 0xf000
	s_addc_u32 s5, s71, 0
	global_store_short v145, v40, s[4:5] offset:64
	s_add_u32 s4, s4, 0x300
	s_addc_u32 s5, s5, 0
	global_store_short_d16_hi v145, v40, s[4:5] offset:64
	s_add_u32 s4, s70, 0xf600
	s_addc_u32 s5, s71, 0
	global_store_short v145, v42, s[4:5] offset:64
	s_add_u32 s4, s4, 0x300
	s_addc_u32 s5, s5, 0
	global_store_short_d16_hi v145, v42, s[4:5] offset:64
	s_add_u32 s4, s70, 0x10800
	s_addc_u32 s5, s71, 0
	global_store_short v145, v44, s[4:5] offset:64
	s_add_u32 s4, s4, 0x300
	s_addc_u32 s5, s5, 0
	global_store_short_d16_hi v145, v44, s[4:5] offset:64
	s_add_u32 s4, s70, 0x10e00
	s_addc_u32 s5, s71, 0
	global_store_short v145, v46, s[4:5] offset:64
	s_add_u32 s4, s4, 0x300
	s_addc_u32 s5, s5, 0
	global_store_short_d16_hi v145, v46, s[4:5] offset:64
	v_mad_u32_u24 v128, v132, 32, v131
	ds_read_b64 v[112:113], v128
	v_mad_u32_u24 v128, v132, 33, v131
	ds_read_b64 v[114:115], v128
	v_mad_u32_u24 v128, v132, 34, v131
	ds_read_b64 v[116:117], v128
	v_mad_u32_u24 v128, v132, 35, v131
	ds_read_b64 v[118:119], v128
	v_mad_u32_u24 v128, v132, 40, v131
	ds_read_b64 v[120:121], v128
	v_mad_u32_u24 v128, v132, 41, v131
	ds_read_b64 v[122:123], v128
	v_mad_u32_u24 v128, v132, 42, v131
	ds_read_b64 v[124:125], v128
	v_mad_u32_u24 v128, v132, 43, v131
	ds_read_b64 v[126:127], v128
	v_mad_u32_u24 v128, v132, 48, v131
	ds_read_b64 v[80:81], v128
	v_mad_u32_u24 v128, v132, 49, v131
	ds_read_b64 v[82:83], v128
	v_mad_u32_u24 v128, v132, 50, v131
	ds_read_b64 v[84:85], v128
	v_mad_u32_u24 v128, v132, 51, v131
	ds_read_b64 v[86:87], v128
	v_mad_u32_u24 v128, v132, 56, v131
	ds_read_b64 v[88:89], v128
	v_mad_u32_u24 v128, v132, 57, v131
	ds_read_b64 v[90:91], v128
	v_mad_u32_u24 v128, v132, 58, v131
	ds_read_b64 v[92:93], v128
	v_mad_u32_u24 v128, v132, 59, v131
	ds_read_b64 v[94:95], v128
	v_mov_b32_dpp v48, v0 row_ror:8 row_mask:0xf bank_mask:0xf
	v_mov_b32_dpp v49, v1 row_ror:8 row_mask:0xf bank_mask:0xf
	v_mov_b32_dpp v50, v2 row_ror:8 row_mask:0xf bank_mask:0xf
	v_mov_b32_dpp v51, v3 row_ror:8 row_mask:0xf bank_mask:0xf
	v_mov_b32_dpp v52, v4 row_ror:8 row_mask:0xf bank_mask:0xf
	v_mov_b32_dpp v53, v5 row_ror:8 row_mask:0xf bank_mask:0xf
	v_mov_b32_dpp v54, v6 row_ror:8 row_mask:0xf bank_mask:0xf
	v_mov_b32_dpp v55, v7 row_ror:8 row_mask:0xf bank_mask:0xf
	v_mov_b32_dpp v56, v8 row_ror:8 row_mask:0xf bank_mask:0xf
	v_mov_b32_dpp v57, v9 row_ror:8 row_mask:0xf bank_mask:0xf
	v_mov_b32_dpp v58, v10 row_ror:8 row_mask:0xf bank_mask:0xf
	v_mov_b32_dpp v59, v11 row_ror:8 row_mask:0xf bank_mask:0xf
	v_mov_b32_dpp v60, v12 row_ror:8 row_mask:0xf bank_mask:0xf
	v_mov_b32_dpp v61, v13 row_ror:8 row_mask:0xf bank_mask:0xf
	v_mov_b32_dpp v62, v14 row_ror:8 row_mask:0xf bank_mask:0xf
	v_mov_b32_dpp v63, v15 row_ror:8 row_mask:0xf bank_mask:0xf
	s_waitcnt lgkmcnt(0)
	v_cndmask_b32_e64 v48, v48, -v48, s[36:37]
	v_mul_f32_e32 v0, v0, v112
	v_mul_f32_e32 v48, v113, v48
	v_add_f32_e32 v0, v0, v48
	v_mul_f32_e32 v0, 0x3e16c740, v0
	v_cndmask_b32_e64 v49, v49, -v49, s[36:37]
	v_mul_f32_e32 v1, v1, v114
	v_mul_f32_e32 v49, v115, v49
	v_add_f32_e32 v1, v1, v49
	v_mul_f32_e32 v1, 0x3e16c740, v1
	v_cndmask_b32_e64 v50, v50, -v50, s[36:37]
	v_mul_f32_e32 v2, v2, v116
	v_mul_f32_e32 v50, v117, v50
	v_add_f32_e32 v2, v2, v50
	v_mul_f32_e32 v2, 0x3e16c740, v2
	v_cndmask_b32_e64 v51, v51, -v51, s[36:37]
	v_mul_f32_e32 v3, v3, v118
	v_mul_f32_e32 v51, v119, v51
	v_add_f32_e32 v3, v3, v51
	v_mul_f32_e32 v3, 0x3e16c740, v3
	v_cndmask_b32_e64 v52, v52, -v52, s[36:37]
	v_mul_f32_e32 v4, v4, v120
	v_mul_f32_e32 v52, v121, v52
	v_add_f32_e32 v4, v4, v52
	v_mul_f32_e32 v4, 0x3e16c740, v4
	v_cndmask_b32_e64 v53, v53, -v53, s[36:37]
	v_mul_f32_e32 v5, v5, v122
	v_mul_f32_e32 v53, v123, v53
	v_add_f32_e32 v5, v5, v53
	v_mul_f32_e32 v5, 0x3e16c740, v5
	v_cndmask_b32_e64 v54, v54, -v54, s[36:37]
	v_mul_f32_e32 v6, v6, v124
	v_mul_f32_e32 v54, v125, v54
	v_add_f32_e32 v6, v6, v54
	v_mul_f32_e32 v6, 0x3e16c740, v6
	v_cndmask_b32_e64 v55, v55, -v55, s[36:37]
	v_mul_f32_e32 v7, v7, v126
	v_mul_f32_e32 v55, v127, v55
	v_add_f32_e32 v7, v7, v55
	v_mul_f32_e32 v7, 0x3e16c740, v7
	v_cndmask_b32_e64 v56, v56, -v56, s[36:37]
	v_mul_f32_e32 v8, v8, v80
	v_mul_f32_e32 v56, v81, v56
	v_add_f32_e32 v8, v8, v56
	v_mul_f32_e32 v8, 0x3e16c740, v8
	v_cndmask_b32_e64 v57, v57, -v57, s[36:37]
	v_mul_f32_e32 v9, v9, v82
	v_mul_f32_e32 v57, v83, v57
	v_add_f32_e32 v9, v9, v57
	v_mul_f32_e32 v9, 0x3e16c740, v9
	v_cndmask_b32_e64 v58, v58, -v58, s[36:37]
	v_mul_f32_e32 v10, v10, v84
	v_mul_f32_e32 v58, v85, v58
	v_add_f32_e32 v10, v10, v58
	v_mul_f32_e32 v10, 0x3e16c740, v10
	v_cndmask_b32_e64 v59, v59, -v59, s[36:37]
	v_mul_f32_e32 v11, v11, v86
	v_mul_f32_e32 v59, v87, v59
	v_add_f32_e32 v11, v11, v59
	v_mul_f32_e32 v11, 0x3e16c740, v11
	v_cndmask_b32_e64 v60, v60, -v60, s[36:37]
	v_mul_f32_e32 v12, v12, v88
	v_mul_f32_e32 v60, v89, v60
	v_add_f32_e32 v12, v12, v60
	v_mul_f32_e32 v12, 0x3e16c740, v12
	v_cndmask_b32_e64 v61, v61, -v61, s[36:37]
	v_mul_f32_e32 v13, v13, v90
	v_mul_f32_e32 v61, v91, v61
	v_add_f32_e32 v13, v13, v61
	v_mul_f32_e32 v13, 0x3e16c740, v13
	v_cndmask_b32_e64 v62, v62, -v62, s[36:37]
	v_mul_f32_e32 v14, v14, v92
	v_mul_f32_e32 v62, v93, v62
	v_add_f32_e32 v14, v14, v62
	v_mul_f32_e32 v14, 0x3e16c740, v14
	v_cndmask_b32_e64 v63, v63, -v63, s[36:37]
	v_mul_f32_e32 v15, v15, v94
	v_mul_f32_e32 v63, v95, v63
	v_add_f32_e32 v15, v15, v63
	v_mul_f32_e32 v15, 0x3e16c740, v15
	v_cvt_pk_bf16_f32 v0, v0, v1
	v_cvt_pk_bf16_f32 v2, v2, v3
	v_cvt_pk_bf16_f32 v4, v4, v5
	v_cvt_pk_bf16_f32 v6, v6, v7
	v_cvt_pk_bf16_f32 v8, v8, v9
	v_cvt_pk_bf16_f32 v10, v10, v11
	v_cvt_pk_bf16_f32 v12, v12, v13
	v_cvt_pk_bf16_f32 v14, v14, v15
	s_add_u32 s4, s70, 0x12000
	s_addc_u32 s5, s71, 0
	global_store_short v145, v0, s[4:5] offset:64
	s_add_u32 s4, s4, 0x300
	s_addc_u32 s5, s5, 0
	global_store_short_d16_hi v145, v0, s[4:5] offset:64
	s_add_u32 s4, s70, 0x12600
	s_addc_u32 s5, s71, 0
	global_store_short v145, v2, s[4:5] offset:64
	s_add_u32 s4, s4, 0x300
	s_addc_u32 s5, s5, 0
	global_store_short_d16_hi v145, v2, s[4:5] offset:64
	s_add_u32 s4, s70, 0x13800
	s_addc_u32 s5, s71, 0
	global_store_short v145, v4, s[4:5] offset:64
	s_add_u32 s4, s4, 0x300
	s_addc_u32 s5, s5, 0
	global_store_short_d16_hi v145, v4, s[4:5] offset:64
	s_add_u32 s4, s70, 0x13e00
	s_addc_u32 s5, s71, 0
	global_store_short v145, v6, s[4:5] offset:64
	s_add_u32 s4, s4, 0x300
	s_addc_u32 s5, s5, 0
	global_store_short_d16_hi v145, v6, s[4:5] offset:64
	s_add_u32 s4, s70, 0x15000
	s_addc_u32 s5, s71, 0
	global_store_short v145, v8, s[4:5] offset:64
	s_add_u32 s4, s4, 0x300
	s_addc_u32 s5, s5, 0
	global_store_short_d16_hi v145, v8, s[4:5] offset:64
	s_add_u32 s4, s70, 0x15600
	s_addc_u32 s5, s71, 0
	global_store_short v145, v10, s[4:5] offset:64
	s_add_u32 s4, s4, 0x300
	s_addc_u32 s5, s5, 0
	global_store_short_d16_hi v145, v10, s[4:5] offset:64
	s_add_u32 s4, s70, 0x16800
	s_addc_u32 s5, s71, 0
	global_store_short v145, v12, s[4:5] offset:64
	s_add_u32 s4, s4, 0x300
	s_addc_u32 s5, s5, 0
	global_store_short_d16_hi v145, v12, s[4:5] offset:64
	s_add_u32 s4, s70, 0x16e00
	s_addc_u32 s5, s71, 0
	global_store_short v145, v14, s[4:5] offset:64
	s_add_u32 s4, s4, 0x300
	s_addc_u32 s5, s5, 0
	global_store_short_d16_hi v145, v14, s[4:5] offset:64
	s_branch .LBB0_1223

.LBB0_1421:
	v_lshl_add_u64 v[130:131], v[146:147], 1, s[58:59]
	v_mad_u64_u32 v[132:133], s[4:5], s4, v142, 0
	v_lshl_add_u64 v[130:131], v[132:133], 1, v[130:131]
	v_lshl_add_u64 v[130:131], s[60:61], 1, v[130:131]
	v_lshl_add_u64 v[130:131], v[134:135], 1, v[130:131]
	v_mov_b32_e32 v145, v129
	v_lshl_add_u64 v[144:145], v[130:131], 0, v[144:145]
	v_cvt_pk_bf16_f32 v130, v0, v1
	v_cvt_pk_bf16_f32 v131, v2, v3
	v_cvt_pk_bf16_f32 v132, v4, v5
	v_cvt_pk_bf16_f32 v133, v6, v7
	global_store_dwordx4 v[144:145], v[130:133], off offset:192
	s_nop 1
	v_cvt_pk_bf16_f32 v130, v8, v9
	v_cvt_pk_bf16_f32 v131, v10, v11
	v_cvt_pk_bf16_f32 v132, v12, v13
	v_cvt_pk_bf16_f32 v133, v14, v15
	global_store_dwordx4 v[144:145], v[130:133], off offset:224
	s_andn2_saveexec_b64 s[4:5], s[6:7]
	s_cbranch_execnz .LBB0_1275
	s_branch .LBB0_1276
.LBB0_1561:
	s_mov_b64 s[0:1], 0

.LBB0_1662:
	v_lshlrev_b64 v[2:3], 12, v[2:3]
	v_lshl_add_u64 v[0:1], v[0:1], 0, v[2:3]
	v_lshlrev_b32_e32 v2, 2, v16
	v_and_b32_e32 v32, 0xfc, v2
	v_lshlrev_b32_e32 v128, 2, v32
	v_lshl_add_u64 v[0:1], v[0:1], 0, v[128:129]
	global_load_dwordx4 v[12:15], v[0:1], off nt
	global_load_dwordx4 v[8:11], v[0:1], off offset:1024 nt
	global_load_dwordx4 v[4:7], v[0:1], off offset:2048 nt
	s_nop 0
	global_load_dwordx4 v[0:3], v[0:1], off offset:3072 nt
	v_and_b32_e32 v17, 64, v226
	v_add_u32_e32 v17, 64, v17
	v_xor_b32_e32 v18, 32, v226
	v_cmp_lt_i32_e32 vcc, v18, v17
	s_load_dword s4, s[24:25], 0x0
	v_readlane_b32 s6, v254, 46
	v_cndmask_b32_e32 v18, v226, v18, vcc
	v_lshlrev_b32_e32 v33, 2, v18
	v_xor_b32_e32 v18, 16, v226
	v_cmp_lt_i32_e32 vcc, v18, v17
	v_readlane_b32 s7, v254, 47
	v_lshlrev_b64 v[24:25], 11, v[36:37]
	v_cndmask_b32_e32 v18, v226, v18, vcc
	v_lshlrev_b32_e32 v50, 2, v18
	v_xor_b32_e32 v18, 8, v226
	v_cmp_lt_i32_e32 vcc, v18, v17
	v_and_b32_e32 v16, 63, v16
	s_waitcnt lgkmcnt(0)
	s_lshl_b32 s4, s4, 3
	v_cndmask_b32_e32 v18, v226, v18, vcc
	v_lshlrev_b32_e32 v51, 2, v18
	v_xor_b32_e32 v18, 4, v226
	v_cmp_lt_i32_e32 vcc, v18, v17
	v_lshl_add_u64 v[34:35], s[6:7], 0, v[128:129]
	v_lshl_add_u64 v[24:25], s[74:75], 0, v[24:25]
	v_cndmask_b32_e32 v18, v226, v18, vcc
	v_lshlrev_b32_e32 v52, 2, v18
	v_xor_b32_e32 v18, 2, v226
	v_cmp_lt_i32_e32 vcc, v18, v17
	v_lshlrev_b32_e32 v128, 3, v16
	v_readlane_b32 s6, v253, 31
	v_cndmask_b32_e32 v18, v226, v18, vcc
	v_lshlrev_b32_e32 v53, 2, v18
	v_xor_b32_e32 v18, 1, v226
	v_cmp_lt_i32_e32 vcc, v18, v17
	v_or_b32_e32 v20, 0x200, v32
	v_or_b32_e32 v22, 0x300, v32
	v_cndmask_b32_e32 v17, v226, v18, vcc
	v_lshlrev_b32_e32 v54, 2, v17
	v_or_b32_e32 v18, 0x100, v32
	v_add_u32_e32 v38, s4, v36
	s_ashr_i32 s5, s4, 31
	v_lshl_add_u64 v[16:17], v[24:25], 0, v[128:129]
	v_readlane_b32 s7, v253, 32
	v_ashrrev_i32_e32 v39, 31, v38
	s_lshl_b64 s[30:31], s[4:5], 11
	v_lshl_add_u64 v[40:41], s[6:7], 0, v[16:17]
	s_mov_b64 s[36:37], 0
	v_lshlrev_b32_e32 v42, 2, v18
	v_lshlrev_b32_e32 v44, 2, v20
	v_lshlrev_b32_e32 v46, 2, v22
	s_waitcnt vmcnt(0)
	s_branch .LBB0_1666

.LBB0_1666:
	s_movk_i32 s6, 0x3000
	v_add_u32_e32 v48, s4, v36
	v_cmp_gt_i32_e32 vcc, s6, v38
	s_waitcnt vmcnt(4)
	v_mov_b32_e32 v19, v3
	v_mov_b32_e32 v18, v2
	v_mov_b32_e32 v17, v1
	v_mov_b32_e32 v16, v0
	v_mov_b32_e32 v23, v7
	v_mov_b32_e32 v22, v6
	v_mov_b32_e32 v21, v5
	v_mov_b32_e32 v20, v4
	v_mov_b32_e32 v27, v11
	v_mov_b32_e32 v26, v10
	v_mov_b32_e32 v25, v9
	v_mov_b32_e32 v24, v8
	v_mov_b32_e32 v31, v15
	v_mov_b32_e32 v30, v14
	v_mov_b32_e32 v29, v13
	v_mov_b32_e32 v28, v12
	s_and_saveexec_b64 s[6:7], vcc
	s_cbranch_execz .LBB0_1665
	v_readlane_b32 s12, v254, 24
	v_readlane_b32 s13, v254, 25
	s_mov_b64 s[8:9], -1
	s_and_b64 vcc, exec, s[12:13]
	s_cbranch_vccz .LBB0_1669
	v_ashrrev_i32_e32 v49, 31, v48
	s_mov_b64 s[8:9], 0
	v_mov_b64_e32 v[16:17], v[48:49]
